# one static s_setprio 1 for waves 4-7 at kernel entry, all remaining per-segment s_setprio flips removed (loops 192/773/797), MFMA segments re-aligned
# baseline (speedup 1.0000x reference)
_Z4mega6Params:
	v_readfirstlane_b32 s4, v0
	s_and_b32 s4, s4, 0x3ff
	s_cmp_lt_u32 s4, 0x100
	s_cbranch_scc1 my_prio_skip
	s_setprio 1
my_prio_skip:
	s_mov_b32 s100, 0
	s_load_dwordx2 s[56:57], s[0:1], 0x100
	s_add_u32 s4, s0, 0x100
	s_addc_u32 s5, s1, 0
	v_and_b32_e32 v186, 0x3ff, v0
	v_writelane_b32 v252, s4, 0
	v_cmp_gt_u32_e32 vcc, 2, v186
	s_nop 0
	v_writelane_b32 v252, s5, 1
	s_and_saveexec_b64 s[4:5], vcc
	v_lshl_add_u32 v1, v186, 2, 0
	v_add_u32_e32 v1, 0x25ff0, v1
	v_mov_b32_e32 v2, 0
	ds_write_b32 v1, v2
	s_or_b64 exec, exec, s[4:5]
	s_mov_b64 s[4:5], s[0:1]
	s_waitcnt lgkmcnt(0)
	s_barrier
	s_load_dwordx2 s[24:25], s[4:5], 0xf8
	s_getreg_b32 s3, hwreg(HW_REG_XCC_ID, 0, 4)
	s_mov_b32 s61, 0
	v_cmp_eq_u32_e64 s[6:7], 0, v186
	s_waitcnt lgkmcnt(0)
	s_add_u32 s26, s24, 0x1df10000
	s_addc_u32 s27, s25, 0
	s_and_b32 s12, s3, 15
	s_lshl_b32 s13, s12, 6
	s_mov_b64 s[4:5], exec
	v_writelane_b32 v252, s6, 2
	s_nop 1
	v_writelane_b32 v252, s7, 3
	s_and_b64 s[6:7], s[4:5], s[6:7]
	s_mov_b64 exec, s[6:7]
	s_cbranch_execz .LBB0_5
	s_mov_b64 s[6:7], exec
	v_mbcnt_lo_u32_b32 v1, s6, 0
	v_mbcnt_hi_u32_b32 v1, s7, v1
	v_cmp_eq_u32_e32 vcc, 0, v1
	s_and_b64 s[8:9], exec, vcc
	s_mov_b64 exec, s[8:9]
	s_cbranch_execz .LBB0_5
	s_lshl_b32 s3, s13, 2
	s_bcnt1_i32_b64 s6, s[6:7]
	v_mov_b32_e32 v1, s3
	v_mov_b32_e32 v2, s6
	global_atomic_add v1, v2, s[26:27] offset:1024

.LBB0_192:
	s_add_u32 s6, s26, s54
	s_addc_u32 s11, s27, s55
	s_add_u32 s6, s6, 0x100
	s_addc_u32 s11, s11, 0
	s_add_u32 s12, s29, s54
	s_addc_u32 s19, s31, s55
	s_add_i32 s23, 0, 0x10000
	v_add_u32_e32 v169, s23, v156
	ds_read_b128 v[146:149], v169
	ds_read_b128 v[170:173], v169 offset:1024
	ds_read_b128 v[174:177], v169 offset:2048
	ds_read_b128 v[178:181], v169 offset:3072
	s_cmpk_eq_i32 s54, 0x700
	s_cselect_b32 s69, s53, s11
	s_cselect_b32 s68, s52, s6
	s_cselect_b32 s59, s49, s19
	s_cselect_b32 s58, s48, s12
	v_lshl_add_u64 v[230:231], v[152:153], 0, s[54:55]
	s_add_i32 m0, s72, 0xc000
	ds_read_b128 v[182:185], v168
	ds_read_b128 v[194:197], v168 offset:1024
	ds_read_b128 v[206:209], v168 offset:2048
	ds_read_b128 v[210:213], v168 offset:3072
	ds_read_b128 v[214:217], v168 offset:4096
	ds_read_b128 v[218:221], v168 offset:5120
	ds_read_b128 v[222:225], v168 offset:6144
	ds_read_b128 v[226:229], v168 offset:7168
	global_load_lds_dwordx4 v[230:231], off
	v_lshl_add_u64 v[230:231], v[154:155], 0, s[54:55]
	s_add_i32 m0, s72, 0xe000
	s_nop 0
	global_load_lds_dwordx4 v[230:231], off
	s_waitcnt lgkmcnt(8)
	s_barrier
	s_waitcnt lgkmcnt(7)
	v_mfma_f32_16x16x32_bf16 v[16:19], v[146:149], v[182:185], v[16:19]
	v_mfma_f32_16x16x32_bf16 v[20:23], v[174:177], v[182:185], v[20:23]
	s_waitcnt lgkmcnt(5)
	v_mfma_f32_16x16x32_bf16 v[40:43], v[146:149], v[206:209], v[40:43]
	v_mfma_f32_16x16x32_bf16 v[32:35], v[174:177], v[206:209], v[32:35]
	s_waitcnt lgkmcnt(3)
	v_mfma_f32_16x16x32_bf16 v[64:67], v[146:149], v[214:217], v[64:67]
	v_mfma_f32_16x16x32_bf16 v[56:59], v[174:177], v[214:217], v[56:59]
	s_waitcnt lgkmcnt(1)
	v_mfma_f32_16x16x32_bf16 v[88:91], v[146:149], v[222:225], v[88:91]
	v_mfma_f32_16x16x32_bf16 v[80:83], v[174:177], v[222:225], v[80:83]
	v_mfma_f32_16x16x32_bf16 v[16:19], v[170:173], v[194:197], v[16:19]
	v_mfma_f32_16x16x32_bf16 v[20:23], v[178:181], v[194:197], v[20:23]
	v_mfma_f32_16x16x32_bf16 v[40:43], v[170:173], v[210:213], v[40:43]
	v_mfma_f32_16x16x32_bf16 v[32:35], v[178:181], v[210:213], v[32:35]
	v_mfma_f32_16x16x32_bf16 v[64:67], v[170:173], v[218:221], v[64:67]
	v_mfma_f32_16x16x32_bf16 v[56:59], v[178:181], v[218:221], v[56:59]
	s_waitcnt lgkmcnt(0)
	v_mfma_f32_16x16x32_bf16 v[88:91], v[170:173], v[226:229], v[88:91]
	v_mfma_f32_16x16x32_bf16 v[80:83], v[178:181], v[226:229], v[80:83]
	s_barrier
	s_add_i32 s6, 0, 0x14000
	s_add_i32 s11, s23, s71
	v_add_u32_e32 v169, s6, v156
	v_lshl_add_u64 v[246:247], s[58:59], 0, v[130:131]
	s_mov_b32 m0, s11
	ds_read_b128 v[230:233], v169
	ds_read_b128 v[234:237], v169 offset:1024
	ds_read_b128 v[238:241], v169 offset:2048
	ds_read_b128 v[242:245], v169 offset:3072
	global_load_lds_dwordx4 v[246:247], off
	v_lshl_add_u64 v[248:249], s[58:59], 0, v[134:135]
	s_add_i32 m0, s11, 0x2000
	s_nop 0
	global_load_lds_dwordx4 v[248:249], off
	s_barrier
	s_waitcnt lgkmcnt(3)
	v_mfma_f32_16x16x32_bf16 v[0:3], v[230:233], v[182:185], v[0:3]
	s_waitcnt lgkmcnt(1)
	v_mfma_f32_16x16x32_bf16 v[4:7], v[238:241], v[182:185], v[4:7]
	v_mfma_f32_16x16x32_bf16 v[8:11], v[230:233], v[206:209], v[8:11]
	v_mfma_f32_16x16x32_bf16 v[12:15], v[238:241], v[206:209], v[12:15]
	v_mfma_f32_16x16x32_bf16 v[24:27], v[230:233], v[214:217], v[24:27]
	v_mfma_f32_16x16x32_bf16 v[28:31], v[238:241], v[214:217], v[28:31]
	v_mfma_f32_16x16x32_bf16 v[48:51], v[230:233], v[222:225], v[48:51]
	v_mfma_f32_16x16x32_bf16 v[52:55], v[238:241], v[222:225], v[52:55]
	v_mfma_f32_16x16x32_bf16 v[0:3], v[234:237], v[194:197], v[0:3]
	s_waitcnt lgkmcnt(0)
	v_mfma_f32_16x16x32_bf16 v[4:7], v[242:245], v[194:197], v[4:7]
	v_mfma_f32_16x16x32_bf16 v[8:11], v[234:237], v[210:213], v[8:11]
	v_mfma_f32_16x16x32_bf16 v[12:15], v[242:245], v[210:213], v[12:15]
	v_mfma_f32_16x16x32_bf16 v[24:27], v[234:237], v[218:221], v[24:27]
	v_mfma_f32_16x16x32_bf16 v[28:31], v[242:245], v[218:221], v[28:31]
	v_mfma_f32_16x16x32_bf16 v[48:51], v[234:237], v[226:229], v[48:51]
	v_mfma_f32_16x16x32_bf16 v[52:55], v[242:245], v[226:229], v[52:55]
	s_mov_b32 m0, s72
	v_lshl_add_u64 v[250:251], s[68:69], 0, v[128:129]
	s_barrier
	ds_read_b128 v[182:185], v168 offset:16384
	ds_read_b128 v[194:197], v168 offset:17408
	ds_read_b128 v[206:209], v168 offset:18432
	ds_read_b128 v[210:213], v168 offset:19456
	ds_read_b128 v[214:217], v168 offset:20480
	ds_read_b128 v[218:221], v168 offset:21504
	ds_read_b128 v[222:225], v168 offset:22528
	ds_read_b128 v[226:229], v168 offset:23552
	global_load_lds_dwordx4 v[250:251], off
	v_lshl_add_u64 v[192:193], s[68:69], 0, v[132:133]
	s_mov_b32 m0, s73
	s_nop 0
	global_load_lds_dwordx4 v[192:193], off
	s_barrier
	s_waitcnt lgkmcnt(7)
	v_mfma_f32_16x16x32_bf16 v[76:79], v[146:149], v[182:185], v[76:79]
	v_mfma_f32_16x16x32_bf16 v[72:75], v[174:177], v[182:185], v[72:75]
	s_waitcnt lgkmcnt(5)
	v_mfma_f32_16x16x32_bf16 v[100:103], v[146:149], v[206:209], v[100:103]
	v_mfma_f32_16x16x32_bf16 v[96:99], v[174:177], v[206:209], v[96:99]
	s_waitcnt lgkmcnt(3)
	v_mfma_f32_16x16x32_bf16 v[116:119], v[146:149], v[214:217], v[116:119]
	v_mfma_f32_16x16x32_bf16 v[112:115], v[174:177], v[214:217], v[112:115]
	s_waitcnt lgkmcnt(1)
	v_mfma_f32_16x16x32_bf16 v[124:127], v[146:149], v[222:225], v[124:127]
	v_mfma_f32_16x16x32_bf16 v[120:123], v[174:177], v[222:225], v[120:123]
	v_mfma_f32_16x16x32_bf16 v[76:79], v[170:173], v[194:197], v[76:79]
	v_mfma_f32_16x16x32_bf16 v[72:75], v[178:181], v[194:197], v[72:75]
	v_mfma_f32_16x16x32_bf16 v[100:103], v[170:173], v[210:213], v[100:103]
	v_mfma_f32_16x16x32_bf16 v[96:99], v[178:181], v[210:213], v[96:99]
	v_mfma_f32_16x16x32_bf16 v[116:119], v[170:173], v[218:221], v[116:119]
	v_mfma_f32_16x16x32_bf16 v[112:115], v[178:181], v[218:221], v[112:115]
	s_waitcnt lgkmcnt(0)
	v_mfma_f32_16x16x32_bf16 v[124:127], v[170:173], v[226:229], v[124:127]
	v_mfma_f32_16x16x32_bf16 v[120:123], v[178:181], v[226:229], v[120:123]
	s_barrier
	s_add_u32 s88, s58, 0x40000
	s_addc_u32 s89, s59, 0
	s_add_i32 s6, s6, s71
	v_lshl_add_u64 v[146:147], s[88:89], 0, v[130:131]
	s_mov_b32 m0, s6
	s_nop 0
	global_load_lds_dwordx4 v[146:147], off
	v_lshl_add_u64 v[146:147], s[88:89], 0, v[134:135]
	s_add_i32 m0, s6, 0x2000
	s_nop 0
	global_load_lds_dwordx4 v[146:147], off
	s_nop 0
	s_waitcnt vmcnt(6)
	s_barrier
	v_mfma_f32_16x16x32_bf16 v[36:39], v[230:233], v[182:185], v[36:39]
	v_mfma_f32_16x16x32_bf16 v[44:47], v[238:241], v[182:185], v[44:47]
	v_mfma_f32_16x16x32_bf16 v[60:63], v[230:233], v[206:209], v[60:63]
	v_mfma_f32_16x16x32_bf16 v[68:71], v[238:241], v[206:209], v[68:71]
	v_mfma_f32_16x16x32_bf16 v[84:87], v[230:233], v[214:217], v[84:87]
	v_mfma_f32_16x16x32_bf16 v[92:95], v[238:241], v[214:217], v[92:95]
	v_mfma_f32_16x16x32_bf16 v[108:111], v[230:233], v[222:225], v[108:111]
	v_mfma_f32_16x16x32_bf16 v[104:107], v[238:241], v[222:225], v[104:107]
	v_mfma_f32_16x16x32_bf16 v[36:39], v[234:237], v[194:197], v[36:39]
	v_mfma_f32_16x16x32_bf16 v[44:47], v[242:245], v[194:197], v[44:47]
	v_mfma_f32_16x16x32_bf16 v[60:63], v[234:237], v[210:213], v[60:63]
	v_mfma_f32_16x16x32_bf16 v[68:71], v[242:245], v[210:213], v[68:71]
	v_mfma_f32_16x16x32_bf16 v[84:87], v[234:237], v[218:221], v[84:87]
	v_mfma_f32_16x16x32_bf16 v[92:95], v[242:245], v[218:221], v[92:95]
	v_mfma_f32_16x16x32_bf16 v[108:111], v[234:237], v[226:229], v[108:111]
	v_mfma_f32_16x16x32_bf16 v[104:107], v[242:245], v[226:229], v[104:107]
	s_add_i32 s6, 0, 0x18000
	v_add_u32_e32 v169, s6, v156
	s_barrier
	ds_read_b128 v[146:149], v169
	ds_read_b128 v[170:173], v169 offset:1024
	ds_read_b128 v[174:177], v169 offset:2048
	ds_read_b128 v[178:181], v169 offset:3072
	s_add_u32 s68, s68, 0x40000
	s_addc_u32 s69, s69, 0
	s_mov_b32 m0, s74
	v_lshl_add_u64 v[230:231], s[68:69], 0, v[128:129]
	ds_read_b128 v[182:185], v168 offset:32768
	ds_read_b128 v[194:197], v168 offset:33792
	ds_read_b128 v[206:209], v168 offset:34816
	ds_read_b128 v[210:213], v168 offset:35840
	ds_read_b128 v[214:217], v168 offset:36864
	ds_read_b128 v[218:221], v168 offset:37888
	ds_read_b128 v[222:225], v168 offset:38912
	ds_read_b128 v[226:229], v168 offset:39936
	global_load_lds_dwordx4 v[230:231], off
	v_lshl_add_u64 v[230:231], s[68:69], 0, v[132:133]
	s_mov_b32 m0, s75
	s_nop 0
	global_load_lds_dwordx4 v[230:231], off
	s_waitcnt lgkmcnt(8)
	s_barrier
	s_waitcnt lgkmcnt(7)
	v_mfma_f32_16x16x32_bf16 v[16:19], v[146:149], v[182:185], v[16:19]
	v_mfma_f32_16x16x32_bf16 v[20:23], v[174:177], v[182:185], v[20:23]
	s_waitcnt lgkmcnt(5)
	v_mfma_f32_16x16x32_bf16 v[40:43], v[146:149], v[206:209], v[40:43]
	v_mfma_f32_16x16x32_bf16 v[32:35], v[174:177], v[206:209], v[32:35]
	s_waitcnt lgkmcnt(3)
	v_mfma_f32_16x16x32_bf16 v[64:67], v[146:149], v[214:217], v[64:67]
	v_mfma_f32_16x16x32_bf16 v[56:59], v[174:177], v[214:217], v[56:59]
	s_waitcnt lgkmcnt(1)
	v_mfma_f32_16x16x32_bf16 v[88:91], v[146:149], v[222:225], v[88:91]
	v_mfma_f32_16x16x32_bf16 v[80:83], v[174:177], v[222:225], v[80:83]
	v_mfma_f32_16x16x32_bf16 v[16:19], v[170:173], v[194:197], v[16:19]
	v_mfma_f32_16x16x32_bf16 v[20:23], v[178:181], v[194:197], v[20:23]
	v_mfma_f32_16x16x32_bf16 v[40:43], v[170:173], v[210:213], v[40:43]
	v_mfma_f32_16x16x32_bf16 v[32:35], v[178:181], v[210:213], v[32:35]
	v_mfma_f32_16x16x32_bf16 v[64:67], v[170:173], v[218:221], v[64:67]
	v_mfma_f32_16x16x32_bf16 v[56:59], v[178:181], v[218:221], v[56:59]
	s_waitcnt lgkmcnt(0)
	v_mfma_f32_16x16x32_bf16 v[88:91], v[170:173], v[226:229], v[88:91]
	v_mfma_f32_16x16x32_bf16 v[80:83], v[178:181], v[226:229], v[80:83]
	s_barrier
	s_add_i32 s11, 0, 0x1c000
	s_add_i32 s6, s6, s71
	v_add_u32_e32 v169, s11, v156
	v_lshl_add_u64 v[246:247], v[246:247], 0, s[36:37]
	s_mov_b32 m0, s6
	ds_read_b128 v[230:233], v169
	ds_read_b128 v[234:237], v169 offset:1024
	ds_read_b128 v[238:241], v169 offset:2048
	ds_read_b128 v[242:245], v169 offset:3072
	global_load_lds_dwordx4 v[246:247], off
	v_lshl_add_u64 v[246:247], v[248:249], 0, s[36:37]
	s_add_i32 m0, s6, 0x2000
	s_nop 0
	global_load_lds_dwordx4 v[246:247], off
	s_barrier
	s_waitcnt lgkmcnt(3)
	v_mfma_f32_16x16x32_bf16 v[0:3], v[230:233], v[182:185], v[0:3]
	s_waitcnt lgkmcnt(1)
	v_mfma_f32_16x16x32_bf16 v[4:7], v[238:241], v[182:185], v[4:7]
	v_mfma_f32_16x16x32_bf16 v[8:11], v[230:233], v[206:209], v[8:11]
	v_mfma_f32_16x16x32_bf16 v[12:15], v[238:241], v[206:209], v[12:15]
	v_mfma_f32_16x16x32_bf16 v[24:27], v[230:233], v[214:217], v[24:27]
	v_mfma_f32_16x16x32_bf16 v[28:31], v[238:241], v[214:217], v[28:31]
	v_mfma_f32_16x16x32_bf16 v[48:51], v[230:233], v[222:225], v[48:51]
	v_mfma_f32_16x16x32_bf16 v[52:55], v[238:241], v[222:225], v[52:55]
	v_mfma_f32_16x16x32_bf16 v[0:3], v[234:237], v[194:197], v[0:3]
	s_waitcnt lgkmcnt(0)
	v_mfma_f32_16x16x32_bf16 v[4:7], v[242:245], v[194:197], v[4:7]
	v_mfma_f32_16x16x32_bf16 v[8:11], v[234:237], v[210:213], v[8:11]
	v_mfma_f32_16x16x32_bf16 v[12:15], v[242:245], v[210:213], v[12:15]
	v_mfma_f32_16x16x32_bf16 v[24:27], v[234:237], v[218:221], v[24:27]
	v_mfma_f32_16x16x32_bf16 v[28:31], v[242:245], v[218:221], v[28:31]
	v_mfma_f32_16x16x32_bf16 v[48:51], v[234:237], v[226:229], v[48:51]
	v_mfma_f32_16x16x32_bf16 v[52:55], v[242:245], v[226:229], v[52:55]
	s_mov_b32 m0, s82
	v_lshl_add_u64 v[246:247], v[250:251], 0, s[36:37]
	s_barrier
	ds_read_b128 v[182:185], v168 offset:49152
	ds_read_b128 v[194:197], v168 offset:50176
	ds_read_b128 v[206:209], v168 offset:51200
	ds_read_b128 v[210:213], v168 offset:52224
	ds_read_b128 v[214:217], v168 offset:53248
	ds_read_b128 v[218:221], v168 offset:54272
	ds_read_b128 v[222:225], v168 offset:55296
	ds_read_b128 v[226:229], v168 offset:56320
	global_load_lds_dwordx4 v[246:247], off
	v_lshl_add_u64 v[192:193], v[192:193], 0, s[36:37]
	s_mov_b32 m0, s83
	s_nop 0
	global_load_lds_dwordx4 v[192:193], off
	s_barrier
	s_waitcnt lgkmcnt(7)
	v_mfma_f32_16x16x32_bf16 v[76:79], v[146:149], v[182:185], v[76:79]
	v_mfma_f32_16x16x32_bf16 v[72:75], v[174:177], v[182:185], v[72:75]
	s_waitcnt lgkmcnt(5)
	v_mfma_f32_16x16x32_bf16 v[100:103], v[146:149], v[206:209], v[100:103]
	v_mfma_f32_16x16x32_bf16 v[96:99], v[174:177], v[206:209], v[96:99]
	s_waitcnt lgkmcnt(3)
	v_mfma_f32_16x16x32_bf16 v[116:119], v[146:149], v[214:217], v[116:119]
	v_mfma_f32_16x16x32_bf16 v[112:115], v[174:177], v[214:217], v[112:115]
	s_waitcnt lgkmcnt(1)
	v_mfma_f32_16x16x32_bf16 v[124:127], v[146:149], v[222:225], v[124:127]
	v_mfma_f32_16x16x32_bf16 v[120:123], v[174:177], v[222:225], v[120:123]
	v_mfma_f32_16x16x32_bf16 v[76:79], v[170:173], v[194:197], v[76:79]
	v_mfma_f32_16x16x32_bf16 v[72:75], v[178:181], v[194:197], v[72:75]
	v_mfma_f32_16x16x32_bf16 v[100:103], v[170:173], v[210:213], v[100:103]
	v_mfma_f32_16x16x32_bf16 v[96:99], v[178:181], v[210:213], v[96:99]
	v_mfma_f32_16x16x32_bf16 v[116:119], v[170:173], v[218:221], v[116:119]
	v_mfma_f32_16x16x32_bf16 v[112:115], v[178:181], v[218:221], v[112:115]
	s_waitcnt lgkmcnt(0)
	v_mfma_f32_16x16x32_bf16 v[124:127], v[170:173], v[226:229], v[124:127]
	v_mfma_f32_16x16x32_bf16 v[120:123], v[178:181], v[226:229], v[120:123]
	s_barrier
	s_add_u32 s58, s58, 0x40080
	s_addc_u32 s59, s59, 0
	s_add_i32 s6, s11, s71
	v_lshl_add_u64 v[146:147], s[58:59], 0, v[130:131]
	s_mov_b32 m0, s6
	s_nop 0
	global_load_lds_dwordx4 v[146:147], off
	v_lshl_add_u64 v[146:147], s[58:59], 0, v[134:135]
	s_add_i32 m0, s6, 0x2000
	s_nop 0
	global_load_lds_dwordx4 v[146:147], off
	s_waitcnt vmcnt(6)
	s_barrier
	v_mfma_f32_16x16x32_bf16 v[36:39], v[230:233], v[182:185], v[36:39]
	v_mfma_f32_16x16x32_bf16 v[44:47], v[238:241], v[182:185], v[44:47]
	v_mfma_f32_16x16x32_bf16 v[60:63], v[230:233], v[206:209], v[60:63]
	v_mfma_f32_16x16x32_bf16 v[68:71], v[238:241], v[206:209], v[68:71]
	v_mfma_f32_16x16x32_bf16 v[84:87], v[230:233], v[214:217], v[84:87]
	v_mfma_f32_16x16x32_bf16 v[92:95], v[238:241], v[214:217], v[92:95]
	v_mfma_f32_16x16x32_bf16 v[108:111], v[230:233], v[222:225], v[108:111]
	v_mfma_f32_16x16x32_bf16 v[104:107], v[238:241], v[222:225], v[104:107]
	v_mfma_f32_16x16x32_bf16 v[36:39], v[234:237], v[194:197], v[36:39]
	v_mfma_f32_16x16x32_bf16 v[44:47], v[242:245], v[194:197], v[44:47]
	v_mfma_f32_16x16x32_bf16 v[60:63], v[234:237], v[210:213], v[60:63]
	v_mfma_f32_16x16x32_bf16 v[68:71], v[242:245], v[210:213], v[68:71]
	v_mfma_f32_16x16x32_bf16 v[84:87], v[234:237], v[218:221], v[84:87]
	v_mfma_f32_16x16x32_bf16 v[92:95], v[242:245], v[218:221], v[92:95]
	v_mfma_f32_16x16x32_bf16 v[108:111], v[234:237], v[226:229], v[108:111]
	v_mfma_f32_16x16x32_bf16 v[104:107], v[242:245], v[226:229], v[104:107]
	s_add_i32 s10, s10, 2
	s_add_u32 s54, s54, 0x100
	s_addc_u32 s55, s55, 0
	s_cmp_gt_u32 s10, 13
	s_barrier
	s_cbranch_scc0 .LBB0_192
	s_lshl_b32 s6, s84, 10
	v_add_u32_e32 v154, s6, v167
	ds_read_b32 v148, v154
	s_mov_b32 s6, 0xff61b1e6
	v_and_b32_e32 v147, 64, v188
	v_xor_b32_e32 v146, 16, v188
	v_add_u32_e32 v147, 64, v147
	s_waitcnt lgkmcnt(0)
	v_mul_f32_e32 v174, v16, v148
	v_mul_f32_e32 v16, v17, v148
	v_max3_f32 v17, v174, s6, v16
	v_mul_f32_e32 v18, v18, v148
	v_mul_f32_e32 v19, v19, v148
	v_max3_f32 v17, v17, v18, v19
	v_mul_f32_e32 v20, v20, v148
	v_mul_f32_e32 v21, v21, v148
	v_max3_f32 v17, v17, v20, v21
	v_mul_f32_e32 v22, v22, v148
	v_mul_f32_e32 v23, v23, v148
	v_max3_f32 v17, v17, v22, v23
	v_mul_f32_e32 v0, v0, v148
	v_mul_f32_e32 v1, v1, v148
	v_max3_f32 v17, v17, v0, v1
	v_mul_f32_e32 v2, v2, v148
	v_mul_f32_e32 v3, v3, v148
	v_cmp_lt_i32_e32 vcc, v146, v147
	v_max3_f32 v17, v17, v2, v3
	v_mul_f32_e32 v4, v4, v148
	v_mul_f32_e32 v5, v5, v148
	v_cndmask_b32_e32 v146, v188, v146, vcc
	v_max3_f32 v17, v17, v4, v5
	v_mul_f32_e32 v6, v6, v148
	v_mul_f32_e32 v7, v7, v148
	v_lshlrev_b32_e32 v152, 2, v146
	v_max3_f32 v17, v17, v6, v7
	ds_bpermute_b32 v146, v152, v17
	v_xor_b32_e32 v148, 32, v188
	v_cmp_lt_i32_e32 vcc, v148, v147
	s_waitcnt lgkmcnt(0)
	v_max_f32_e32 v146, v146, v146
	v_cndmask_b32_e32 v147, v188, v148, vcc
	v_lshlrev_b32_e32 v153, 2, v147
	v_max_f32_e32 v17, v17, v146
	ds_bpermute_b32 v155, v153, v17
	s_and_saveexec_b64 s[54:55], s[42:43]
	s_cbranch_execz .LBB0_195
	s_waitcnt lgkmcnt(0)
	v_max_f32_e32 v146, v155, v155
	v_max_f32_e32 v17, v17, v17
	v_max_f32_e32 v17, v17, v146
	v_add_u32_e32 v146, s85, v157
	ds_write_b32 v146, v17

.Lm4ap_248:
	s_waitcnt lgkmcnt(0)
	s_barrier
	s_nop 0
	v_mfma_f32_16x16x32_bf16 v[124:127], v[128:131], v[162:165], 0
	v_mfma_f32_16x16x32_bf16 v[120:123], v[136:139], v[162:165], 0
	v_mfma_f32_16x16x32_bf16 v[108:111], v[128:131], v[170:173], 0
	v_mfma_f32_16x16x32_bf16 v[104:107], v[136:139], v[170:173], 0
	v_mfma_f32_16x16x32_bf16 v[96:99], v[128:131], v[178:181], 0
	v_mfma_f32_16x16x32_bf16 v[88:91], v[136:139], v[178:181], 0
	v_mfma_f32_16x16x32_bf16 v[84:87], v[128:131], v[194:197], 0
	v_mfma_f32_16x16x32_bf16 v[80:83], v[136:139], v[194:197], 0
	v_mfma_f32_16x16x32_bf16 v[124:127], v[132:135], v[166:169], v[124:127]
	v_mfma_f32_16x16x32_bf16 v[120:123], v[146:149], v[166:169], v[120:123]
	v_mfma_f32_16x16x32_bf16 v[108:111], v[132:135], v[174:177], v[108:111]
	v_mfma_f32_16x16x32_bf16 v[104:107], v[146:149], v[174:177], v[104:107]
	v_mfma_f32_16x16x32_bf16 v[96:99], v[132:135], v[182:185], v[96:99]
	v_mfma_f32_16x16x32_bf16 v[88:91], v[146:149], v[182:185], v[88:91]
	v_mfma_f32_16x16x32_bf16 v[84:87], v[132:135], v[210:213], v[84:87]
	v_mfma_f32_16x16x32_bf16 v[80:83], v[146:149], v[210:213], v[80:83]
	v_mfma_f32_16x16x32_bf16 v[116:119], v[214:217], v[162:165], 0
	v_mfma_f32_16x16x32_bf16 v[112:115], v[222:225], v[162:165], 0
	v_mfma_f32_16x16x32_bf16 v[100:103], v[214:217], v[170:173], 0
	v_mfma_f32_16x16x32_bf16 v[92:95], v[222:225], v[170:173], 0
	v_mfma_f32_16x16x32_bf16 v[76:79], v[214:217], v[178:181], 0
	v_mfma_f32_16x16x32_bf16 v[72:75], v[222:225], v[178:181], 0
	v_mfma_f32_16x16x32_bf16 v[68:71], v[214:217], v[194:197], 0
	v_mfma_f32_16x16x32_bf16 v[64:67], v[222:225], v[194:197], 0
	v_mfma_f32_16x16x32_bf16 v[116:119], v[218:221], v[166:169], v[116:119]
	v_mfma_f32_16x16x32_bf16 v[112:115], v[226:229], v[166:169], v[112:115]
	v_mfma_f32_16x16x32_bf16 v[100:103], v[218:221], v[174:177], v[100:103]
	v_mfma_f32_16x16x32_bf16 v[92:95], v[226:229], v[174:177], v[92:95]
	v_mfma_f32_16x16x32_bf16 v[76:79], v[218:221], v[182:185], v[76:79]
	v_mfma_f32_16x16x32_bf16 v[72:75], v[226:229], v[182:185], v[72:75]
	v_mfma_f32_16x16x32_bf16 v[68:71], v[218:221], v[210:213], v[68:71]
	v_mfma_f32_16x16x32_bf16 v[64:67], v[226:229], v[210:213], v[64:67]
	s_barrier
	s_add_i32 s19, s23, s57
	v_lshl_add_u64 v[230:231], s[54:55], 0, v[140:141]
	s_mov_b32 m0, s19
	s_nop 0
	global_load_lds_dwordx4 v[230:231], off
	v_lshl_add_u64 v[232:233], s[54:55], 0, v[150:151]
	s_add_i32 m0, s19, 0x2000
	s_nop 0
	global_load_lds_dwordx4 v[232:233], off
	s_mov_b32 m0, s68
	v_lshl_add_u64 v[234:235], s[58:59], 0, v[154:155]
	ds_read_b128 v[162:165], v208 offset:16384
	ds_read_b128 v[166:169], v208 offset:17408
	ds_read_b128 v[170:173], v208 offset:18432
	ds_read_b128 v[174:177], v208 offset:19456
	ds_read_b128 v[178:181], v208 offset:20480
	ds_read_b128 v[182:185], v208 offset:21504
	ds_read_b128 v[194:197], v208 offset:22528
	ds_read_b128 v[210:213], v208 offset:23552
	global_load_lds_dwordx4 v[234:235], off
	v_lshl_add_u64 v[236:237], s[58:59], 0, v[152:153]
	s_mov_b32 m0, s69
	s_nop 0
	global_load_lds_dwordx4 v[236:237], off
	s_add_u32 s84, s54, 0x40000
	s_addc_u32 s85, s55, 0
	s_add_i32 s6, s6, s57
	v_lshl_add_u64 v[250:251], s[84:85], 0, v[140:141]
	s_mov_b32 m0, s6
	s_nop 0
	global_load_lds_dwordx4 v[250:251], off
	v_lshl_add_u64 v[250:251], s[84:85], 0, v[150:151]
	s_add_i32 m0, s6, 0x2000
	s_nop 0
	global_load_lds_dwordx4 v[250:251], off
	s_waitcnt vmcnt(40)
	s_cmp_lg_u32 s100, 0
	s_cbranch_scc1 .Lm4bp_248
	s_waitcnt vmcnt(8)

.LBB0_773:
	s_add_u32 s12, s26, s6
	s_addc_u32 s19, s27, 0
	s_add_u32 s23, s12, 0x100
	s_addc_u32 s29, s19, 0
	s_and_b64 s[10:11], s[46:47], exec
	s_cselect_b32 s53, s35, s29
	s_cselect_b32 s52, s34, s23
	s_add_u32 s6, s4, s6
	s_addc_u32 s10, s5, 0
	s_add_u32 s6, s6, 0x100
	s_addc_u32 s23, s10, 0
	s_add_i32 s84, 0, 0x10000
	s_and_b64 s[10:11], s[46:47], exec
	s_cselect_b32 s55, s39, s23
	s_cselect_b32 s54, s38, s6
	s_add_u32 s58, s12, 0x80080
	s_addc_u32 s59, s19, 0
	s_add_i32 s88, s84, s68
	s_add_i32 m0, s69, 0xc000
	s_add_i32 s23, s69, 0xe000
	s_add_i32 s87, 0, 0x14000
	s_add_i32 s86, s88, 0x2000
	s_add_u32 s50, s54, 0x40000
	v_add_u32_e32 v136, s84, v138
	s_addc_u32 s51, s55, 0
	s_add_i32 s29, s87, s68
	ds_read_b128 v[146:149], v136
	ds_read_b128 v[152:155], v136 offset:1024
	ds_read_b128 v[156:159], v136 offset:2048
	ds_read_b128 v[160:163], v136 offset:3072
	s_add_i32 s19, s29, 0x2000
	s_add_i32 s12, 0, 0x18000
	s_add_u32 s48, s52, 0x80000
	s_addc_u32 s49, s53, 0
	s_add_i32 s11, s12, s68
	s_add_i32 s10, 0, 0x1c000
	s_add_i32 s6, s11, 0x2000
	s_add_u32 s46, s54, 0x40080
	s_addc_u32 s47, s55, 0
	s_add_i32 s85, s10, s68
	s_add_i32 s84, s85, 0x2000
	v_lshl_add_u64 v[136:137], s[58:59], 0, v[132:133]
	ds_read_b128 v[164:167], v150
	ds_read_b128 v[168:171], v150 offset:1024
	ds_read_b128 v[172:175], v150 offset:2048
	ds_read_b128 v[176:179], v150 offset:3072
	ds_read_b128 v[180:183], v150 offset:4096
	ds_read_b128 v[194:197], v150 offset:5120
	ds_read_b128 v[206:209], v150 offset:6144
	ds_read_b128 v[210:213], v150 offset:7168
	global_load_lds_dwordx4 v[136:137], off
	v_lshl_add_u64 v[136:137], s[58:59], 0, v[130:131]
	s_mov_b32 m0, s23
	s_nop 0
	global_load_lds_dwordx4 v[136:137], off
	s_waitcnt lgkmcnt(8)
	s_barrier
	s_waitcnt lgkmcnt(7)
	v_mfma_f32_16x16x32_bf16 v[124:127], v[146:149], v[164:167], v[124:127]
	v_mfma_f32_16x16x32_bf16 v[120:123], v[156:159], v[164:167], v[120:123]
	s_waitcnt lgkmcnt(5)
	v_mfma_f32_16x16x32_bf16 v[116:119], v[146:149], v[172:175], v[116:119]
	v_mfma_f32_16x16x32_bf16 v[112:115], v[156:159], v[172:175], v[112:115]
	s_waitcnt lgkmcnt(3)
	v_mfma_f32_16x16x32_bf16 v[108:111], v[146:149], v[180:183], v[108:111]
	v_mfma_f32_16x16x32_bf16 v[104:107], v[156:159], v[180:183], v[104:107]
	s_waitcnt lgkmcnt(1)
	v_mfma_f32_16x16x32_bf16 v[100:103], v[146:149], v[206:209], v[100:103]
	v_mfma_f32_16x16x32_bf16 v[96:99], v[156:159], v[206:209], v[96:99]
	v_mfma_f32_16x16x32_bf16 v[124:127], v[152:155], v[168:171], v[124:127]
	v_mfma_f32_16x16x32_bf16 v[120:123], v[160:163], v[168:171], v[120:123]
	v_mfma_f32_16x16x32_bf16 v[116:119], v[152:155], v[176:179], v[116:119]
	v_mfma_f32_16x16x32_bf16 v[112:115], v[160:163], v[176:179], v[112:115]
	v_mfma_f32_16x16x32_bf16 v[108:111], v[152:155], v[194:197], v[108:111]
	v_mfma_f32_16x16x32_bf16 v[104:107], v[160:163], v[194:197], v[104:107]
	s_waitcnt lgkmcnt(0)
	v_mfma_f32_16x16x32_bf16 v[100:103], v[152:155], v[210:213], v[100:103]
	v_mfma_f32_16x16x32_bf16 v[96:99], v[160:163], v[210:213], v[96:99]
	s_barrier
	v_add_u32_e32 v136, s87, v138
	s_mov_b32 m0, s88
	ds_read_b128 v[214:217], v136
	ds_read_b128 v[218:221], v136 offset:1024
	ds_read_b128 v[222:225], v136 offset:2048
	ds_read_b128 v[226:229], v136 offset:3072
	v_lshl_add_u64 v[136:137], s[54:55], 0, v[140:141]
	global_load_lds_dwordx4 v[136:137], off
	v_lshl_add_u64 v[184:185], s[54:55], 0, v[128:129]
	s_mov_b32 m0, s86
	s_nop 0
	global_load_lds_dwordx4 v[184:185], off
	s_barrier
	s_waitcnt lgkmcnt(3)
	v_mfma_f32_16x16x32_bf16 v[92:95], v[214:217], v[164:167], v[92:95]
	s_waitcnt lgkmcnt(1)
	v_mfma_f32_16x16x32_bf16 v[88:91], v[222:225], v[164:167], v[88:91]
	v_mfma_f32_16x16x32_bf16 v[84:87], v[214:217], v[172:175], v[84:87]
	v_mfma_f32_16x16x32_bf16 v[80:83], v[222:225], v[172:175], v[80:83]
	v_mfma_f32_16x16x32_bf16 v[76:79], v[214:217], v[180:183], v[76:79]
	v_mfma_f32_16x16x32_bf16 v[72:75], v[222:225], v[180:183], v[72:75]
	v_mfma_f32_16x16x32_bf16 v[68:71], v[214:217], v[206:209], v[68:71]
	v_mfma_f32_16x16x32_bf16 v[64:67], v[222:225], v[206:209], v[64:67]
	v_mfma_f32_16x16x32_bf16 v[92:95], v[218:221], v[168:171], v[92:95]
	s_waitcnt lgkmcnt(0)
	v_mfma_f32_16x16x32_bf16 v[88:91], v[226:229], v[168:171], v[88:91]
	v_mfma_f32_16x16x32_bf16 v[84:87], v[218:221], v[176:179], v[84:87]
	v_mfma_f32_16x16x32_bf16 v[80:83], v[226:229], v[176:179], v[80:83]
	v_mfma_f32_16x16x32_bf16 v[76:79], v[218:221], v[194:197], v[76:79]
	v_mfma_f32_16x16x32_bf16 v[72:75], v[226:229], v[194:197], v[72:75]
	v_mfma_f32_16x16x32_bf16 v[68:71], v[218:221], v[210:213], v[68:71]
	v_mfma_f32_16x16x32_bf16 v[64:67], v[226:229], v[210:213], v[64:67]
	s_mov_b32 m0, s69
	v_lshl_add_u64 v[192:193], s[52:53], 0, v[132:133]
	s_barrier
	ds_read_b128 v[164:167], v150 offset:16384
	ds_read_b128 v[168:171], v150 offset:17408
	ds_read_b128 v[172:175], v150 offset:18432
	ds_read_b128 v[176:179], v150 offset:19456
	ds_read_b128 v[180:183], v150 offset:20480
	ds_read_b128 v[194:197], v150 offset:21504
	ds_read_b128 v[206:209], v150 offset:22528
	ds_read_b128 v[210:213], v150 offset:23552
	global_load_lds_dwordx4 v[192:193], off
	v_lshl_add_u64 v[230:231], s[52:53], 0, v[130:131]
	s_mov_b32 m0, s70
	s_nop 0
	global_load_lds_dwordx4 v[230:231], off
	s_barrier
	s_waitcnt lgkmcnt(7)
	v_mfma_f32_16x16x32_bf16 v[60:63], v[146:149], v[164:167], v[60:63]
	v_mfma_f32_16x16x32_bf16 v[56:59], v[156:159], v[164:167], v[56:59]
	s_waitcnt lgkmcnt(5)
	v_mfma_f32_16x16x32_bf16 v[52:55], v[146:149], v[172:175], v[52:55]
	v_mfma_f32_16x16x32_bf16 v[48:51], v[156:159], v[172:175], v[48:51]
	s_waitcnt lgkmcnt(3)
	v_mfma_f32_16x16x32_bf16 v[44:47], v[146:149], v[180:183], v[44:47]
	v_mfma_f32_16x16x32_bf16 v[40:43], v[156:159], v[180:183], v[40:43]
	s_waitcnt lgkmcnt(1)
	v_mfma_f32_16x16x32_bf16 v[36:39], v[146:149], v[206:209], v[36:39]
	v_mfma_f32_16x16x32_bf16 v[32:35], v[156:159], v[206:209], v[32:35]
	v_mfma_f32_16x16x32_bf16 v[60:63], v[152:155], v[168:171], v[60:63]
	v_mfma_f32_16x16x32_bf16 v[56:59], v[160:163], v[168:171], v[56:59]
	v_mfma_f32_16x16x32_bf16 v[52:55], v[152:155], v[176:179], v[52:55]
	v_mfma_f32_16x16x32_bf16 v[48:51], v[160:163], v[176:179], v[48:51]
	v_mfma_f32_16x16x32_bf16 v[44:47], v[152:155], v[194:197], v[44:47]
	v_mfma_f32_16x16x32_bf16 v[40:43], v[160:163], v[194:197], v[40:43]
	s_waitcnt lgkmcnt(0)
	v_mfma_f32_16x16x32_bf16 v[36:39], v[152:155], v[210:213], v[36:39]
	v_mfma_f32_16x16x32_bf16 v[32:35], v[160:163], v[210:213], v[32:35]
	s_barrier
	s_mov_b32 m0, s29
	v_lshl_add_u64 v[146:147], s[50:51], 0, v[140:141]
	global_load_lds_dwordx4 v[146:147], off
	v_lshl_add_u64 v[146:147], s[50:51], 0, v[128:129]
	s_mov_b32 m0, s19
	s_nop 0
	global_load_lds_dwordx4 v[146:147], off
	s_nop 0
	s_waitcnt vmcnt(6)
	s_barrier
	v_mfma_f32_16x16x32_bf16 v[28:31], v[214:217], v[164:167], v[28:31]
	v_mfma_f32_16x16x32_bf16 v[24:27], v[222:225], v[164:167], v[24:27]
	v_mfma_f32_16x16x32_bf16 v[20:23], v[214:217], v[172:175], v[20:23]
	v_mfma_f32_16x16x32_bf16 v[16:19], v[222:225], v[172:175], v[16:19]
	v_mfma_f32_16x16x32_bf16 v[12:15], v[214:217], v[180:183], v[12:15]
	v_mfma_f32_16x16x32_bf16 v[8:11], v[222:225], v[180:183], v[8:11]
	v_mfma_f32_16x16x32_bf16 v[4:7], v[214:217], v[206:209], v[4:7]
	v_mfma_f32_16x16x32_bf16 v[0:3], v[222:225], v[206:209], v[0:3]
	v_mfma_f32_16x16x32_bf16 v[28:31], v[218:221], v[168:171], v[28:31]
	v_mfma_f32_16x16x32_bf16 v[24:27], v[226:229], v[168:171], v[24:27]
	v_mfma_f32_16x16x32_bf16 v[20:23], v[218:221], v[176:179], v[20:23]
	v_mfma_f32_16x16x32_bf16 v[16:19], v[226:229], v[176:179], v[16:19]
	v_mfma_f32_16x16x32_bf16 v[12:15], v[218:221], v[194:197], v[12:15]
	v_mfma_f32_16x16x32_bf16 v[8:11], v[226:229], v[194:197], v[8:11]
	v_mfma_f32_16x16x32_bf16 v[4:7], v[218:221], v[210:213], v[4:7]
	v_mfma_f32_16x16x32_bf16 v[0:3], v[226:229], v[210:213], v[0:3]
	v_add_u32_e32 v151, s12, v138
	s_barrier
	ds_read_b128 v[146:149], v151
	ds_read_b128 v[152:155], v151 offset:1024
	ds_read_b128 v[156:159], v151 offset:2048
	ds_read_b128 v[160:163], v151 offset:3072
	s_mov_b32 m0, s71
	v_lshl_add_u64 v[214:215], s[48:49], 0, v[132:133]
	ds_read_b128 v[164:167], v150 offset:32768
	ds_read_b128 v[168:171], v150 offset:33792
	ds_read_b128 v[172:175], v150 offset:34816
	ds_read_b128 v[176:179], v150 offset:35840
	ds_read_b128 v[180:183], v150 offset:36864
	ds_read_b128 v[194:197], v150 offset:37888
	ds_read_b128 v[206:209], v150 offset:38912
	ds_read_b128 v[210:213], v150 offset:39936
	global_load_lds_dwordx4 v[214:215], off
	v_lshl_add_u64 v[214:215], s[48:49], 0, v[130:131]
	s_mov_b32 m0, s72
	s_nop 0
	global_load_lds_dwordx4 v[214:215], off
	s_waitcnt lgkmcnt(8)
	s_barrier
	s_waitcnt lgkmcnt(7)
	v_mfma_f32_16x16x32_bf16 v[124:127], v[146:149], v[164:167], v[124:127]
	v_mfma_f32_16x16x32_bf16 v[120:123], v[156:159], v[164:167], v[120:123]
	s_waitcnt lgkmcnt(5)
	v_mfma_f32_16x16x32_bf16 v[116:119], v[146:149], v[172:175], v[116:119]
	v_mfma_f32_16x16x32_bf16 v[112:115], v[156:159], v[172:175], v[112:115]
	s_waitcnt lgkmcnt(3)
	v_mfma_f32_16x16x32_bf16 v[108:111], v[146:149], v[180:183], v[108:111]
	v_mfma_f32_16x16x32_bf16 v[104:107], v[156:159], v[180:183], v[104:107]
	s_waitcnt lgkmcnt(1)
	v_mfma_f32_16x16x32_bf16 v[100:103], v[146:149], v[206:209], v[100:103]
	v_mfma_f32_16x16x32_bf16 v[96:99], v[156:159], v[206:209], v[96:99]
	v_mfma_f32_16x16x32_bf16 v[124:127], v[152:155], v[168:171], v[124:127]
	v_mfma_f32_16x16x32_bf16 v[120:123], v[160:163], v[168:171], v[120:123]
	v_mfma_f32_16x16x32_bf16 v[116:119], v[152:155], v[176:179], v[116:119]
	v_mfma_f32_16x16x32_bf16 v[112:115], v[160:163], v[176:179], v[112:115]
	v_mfma_f32_16x16x32_bf16 v[108:111], v[152:155], v[194:197], v[108:111]
	v_mfma_f32_16x16x32_bf16 v[104:107], v[160:163], v[194:197], v[104:107]
	s_waitcnt lgkmcnt(0)
	v_mfma_f32_16x16x32_bf16 v[100:103], v[152:155], v[210:213], v[100:103]
	v_mfma_f32_16x16x32_bf16 v[96:99], v[160:163], v[210:213], v[96:99]
	s_barrier
	s_mov_b32 m0, s11
	v_add_u32_e32 v151, s10, v138
	v_lshl_add_u64 v[136:137], v[136:137], 0, s[36:37]
	ds_read_b128 v[214:217], v151
	ds_read_b128 v[218:221], v151 offset:1024
	ds_read_b128 v[222:225], v151 offset:2048
	ds_read_b128 v[226:229], v151 offset:3072
	global_load_lds_dwordx4 v[136:137], off
	v_lshl_add_u64 v[136:137], v[184:185], 0, s[36:37]
	s_mov_b32 m0, s6
	s_nop 0
	global_load_lds_dwordx4 v[136:137], off
	s_barrier
	s_waitcnt lgkmcnt(3)
	v_mfma_f32_16x16x32_bf16 v[92:95], v[214:217], v[164:167], v[92:95]
	s_waitcnt lgkmcnt(1)
	v_mfma_f32_16x16x32_bf16 v[88:91], v[222:225], v[164:167], v[88:91]
	v_mfma_f32_16x16x32_bf16 v[84:87], v[214:217], v[172:175], v[84:87]
	v_mfma_f32_16x16x32_bf16 v[80:83], v[222:225], v[172:175], v[80:83]
	v_mfma_f32_16x16x32_bf16 v[76:79], v[214:217], v[180:183], v[76:79]
	v_mfma_f32_16x16x32_bf16 v[72:75], v[222:225], v[180:183], v[72:75]
	v_mfma_f32_16x16x32_bf16 v[68:71], v[214:217], v[206:209], v[68:71]
	v_mfma_f32_16x16x32_bf16 v[64:67], v[222:225], v[206:209], v[64:67]
	v_mfma_f32_16x16x32_bf16 v[92:95], v[218:221], v[168:171], v[92:95]
	s_waitcnt lgkmcnt(0)
	v_mfma_f32_16x16x32_bf16 v[88:91], v[226:229], v[168:171], v[88:91]
	v_mfma_f32_16x16x32_bf16 v[84:87], v[218:221], v[176:179], v[84:87]
	v_mfma_f32_16x16x32_bf16 v[80:83], v[226:229], v[176:179], v[80:83]
	v_mfma_f32_16x16x32_bf16 v[76:79], v[218:221], v[194:197], v[76:79]
	v_mfma_f32_16x16x32_bf16 v[72:75], v[226:229], v[194:197], v[72:75]
	v_mfma_f32_16x16x32_bf16 v[68:71], v[218:221], v[210:213], v[68:71]
	v_mfma_f32_16x16x32_bf16 v[64:67], v[226:229], v[210:213], v[64:67]
	s_mov_b32 m0, s75
	v_lshl_add_u64 v[136:137], v[192:193], 0, s[36:37]
	s_barrier
	ds_read_b128 v[164:167], v150 offset:49152
	ds_read_b128 v[168:171], v150 offset:50176
	ds_read_b128 v[172:175], v150 offset:51200
	ds_read_b128 v[176:179], v150 offset:52224
	ds_read_b128 v[180:183], v150 offset:53248
	ds_read_b128 v[194:197], v150 offset:54272
	ds_read_b128 v[206:209], v150 offset:55296
	ds_read_b128 v[210:213], v150 offset:56320
	global_load_lds_dwordx4 v[136:137], off
	v_lshl_add_u64 v[136:137], v[230:231], 0, s[36:37]
	s_mov_b32 m0, s76
	s_nop 0
	global_load_lds_dwordx4 v[136:137], off
	s_barrier
	s_waitcnt lgkmcnt(7)
	v_mfma_f32_16x16x32_bf16 v[60:63], v[146:149], v[164:167], v[60:63]
	v_mfma_f32_16x16x32_bf16 v[56:59], v[156:159], v[164:167], v[56:59]
	s_waitcnt lgkmcnt(5)
	v_mfma_f32_16x16x32_bf16 v[52:55], v[146:149], v[172:175], v[52:55]
	v_mfma_f32_16x16x32_bf16 v[48:51], v[156:159], v[172:175], v[48:51]
	s_waitcnt lgkmcnt(3)
	v_mfma_f32_16x16x32_bf16 v[44:47], v[146:149], v[180:183], v[44:47]
	v_mfma_f32_16x16x32_bf16 v[40:43], v[156:159], v[180:183], v[40:43]
	s_waitcnt lgkmcnt(1)
	v_mfma_f32_16x16x32_bf16 v[36:39], v[146:149], v[206:209], v[36:39]
	v_mfma_f32_16x16x32_bf16 v[32:35], v[156:159], v[206:209], v[32:35]
	v_mfma_f32_16x16x32_bf16 v[60:63], v[152:155], v[168:171], v[60:63]
	v_mfma_f32_16x16x32_bf16 v[56:59], v[160:163], v[168:171], v[56:59]
	v_mfma_f32_16x16x32_bf16 v[52:55], v[152:155], v[176:179], v[52:55]
	v_mfma_f32_16x16x32_bf16 v[48:51], v[160:163], v[176:179], v[48:51]
	v_mfma_f32_16x16x32_bf16 v[44:47], v[152:155], v[194:197], v[44:47]
	v_mfma_f32_16x16x32_bf16 v[40:43], v[160:163], v[194:197], v[40:43]
	s_waitcnt lgkmcnt(0)
	v_mfma_f32_16x16x32_bf16 v[36:39], v[152:155], v[210:213], v[36:39]
	v_mfma_f32_16x16x32_bf16 v[32:35], v[160:163], v[210:213], v[32:35]
	s_barrier
	s_mov_b32 m0, s85
	v_lshl_add_u64 v[136:137], s[46:47], 0, v[140:141]
	global_load_lds_dwordx4 v[136:137], off
	v_lshl_add_u64 v[136:137], s[46:47], 0, v[128:129]
	s_mov_b32 m0, s84
	s_nop 0
	global_load_lds_dwordx4 v[136:137], off
	s_nop 0
	s_waitcnt vmcnt(6)
	s_barrier
	v_mfma_f32_16x16x32_bf16 v[28:31], v[214:217], v[164:167], v[28:31]
	v_mfma_f32_16x16x32_bf16 v[24:27], v[222:225], v[164:167], v[24:27]
	v_mfma_f32_16x16x32_bf16 v[20:23], v[214:217], v[172:175], v[20:23]
	v_mfma_f32_16x16x32_bf16 v[16:19], v[222:225], v[172:175], v[16:19]
	v_mfma_f32_16x16x32_bf16 v[12:15], v[214:217], v[180:183], v[12:15]
	v_mfma_f32_16x16x32_bf16 v[8:11], v[222:225], v[180:183], v[8:11]
	v_mfma_f32_16x16x32_bf16 v[4:7], v[214:217], v[206:209], v[4:7]
	v_mfma_f32_16x16x32_bf16 v[0:3], v[222:225], v[206:209], v[0:3]
	v_mfma_f32_16x16x32_bf16 v[28:31], v[218:221], v[168:171], v[28:31]
	v_mfma_f32_16x16x32_bf16 v[24:27], v[226:229], v[168:171], v[24:27]
	v_mfma_f32_16x16x32_bf16 v[20:23], v[218:221], v[176:179], v[20:23]
	v_mfma_f32_16x16x32_bf16 v[16:19], v[226:229], v[176:179], v[16:19]
	v_mfma_f32_16x16x32_bf16 v[12:15], v[218:221], v[194:197], v[12:15]
	v_mfma_f32_16x16x32_bf16 v[8:11], v[226:229], v[194:197], v[8:11]
	v_mfma_f32_16x16x32_bf16 v[4:7], v[218:221], v[210:213], v[4:7]
	v_mfma_f32_16x16x32_bf16 v[0:3], v[226:229], v[210:213], v[0:3]
	s_movk_i32 s6, 0x100
	s_andn2_b64 vcc, exec, s[44:45]
	s_mov_b64 s[46:47], -1
	s_mov_b64 s[44:45], 0
	s_barrier
	s_cbranch_vccz .LBB0_773
	s_ashr_i32 s10, s81, 2
	s_ashr_i32 s11, s10, 31
	s_lshl_b64 s[10:11], s[10:11], 21
	s_add_u32 s6, s73, s10
	s_addc_u32 s11, s74, s11
	s_lshl_b32 s10, s81, 19
	s_and_b32 s10, s10, 0x180000
	s_add_u32 s10, s6, s10
	v_lshl_or_b32 v136, s77, 8, v139
	s_addc_u32 s11, s11, 0
	v_ashrrev_i32_e32 v137, 31, v136
	v_lshl_add_u64 v[136:137], v[136:137], 1, s[10:11]
	v_pk_mul_f32 v[148:149], v[126:127], s[40:41] op_sel_hi:[1,0]
	v_pk_mul_f32 v[146:147], v[124:125], s[40:41] op_sel_hi:[1,0]
	v_pk_mul_f32 v[152:153], v[122:123], s[40:41] op_sel_hi:[1,0]
	v_pk_mul_f32 v[154:155], v[120:121], s[40:41] op_sel_hi:[1,0]
	v_lshl_add_u64 v[136:137], v[136:137], 0, v[134:135]
	v_cvt_pk_bf16_f32 v146, v146, v147
	v_cvt_pk_bf16_f32 v147, v148, v149
	v_cvt_pk_bf16_f32 v148, v154, v155
	v_cvt_pk_bf16_f32 v149, v152, v153
	global_store_dwordx4 v[136:137], v[146:149], off
	v_pk_mul_f32 v[152:153], v[90:91], s[40:41] op_sel_hi:[1,0]
	v_pk_mul_f32 v[154:155], v[88:89], s[40:41] op_sel_hi:[1,0]
	v_pk_mul_f32 v[148:149], v[94:95], s[40:41] op_sel_hi:[1,0]
	v_pk_mul_f32 v[146:147], v[92:93], s[40:41] op_sel_hi:[1,0]
	v_pk_mul_f32 v[156:157], v[80:81], s[40:41] op_sel_hi:[1,0]
	v_cvt_pk_bf16_f32 v146, v146, v147
	v_cvt_pk_bf16_f32 v147, v148, v149
	v_cvt_pk_bf16_f32 v148, v154, v155
	v_cvt_pk_bf16_f32 v149, v152, v153
	global_store_dwordx4 v[136:137], v[146:149], off offset:256
	v_pk_mul_f32 v[152:153], v[114:115], s[40:41] op_sel_hi:[1,0]
	v_pk_mul_f32 v[154:155], v[112:113], s[40:41] op_sel_hi:[1,0]
	v_pk_mul_f32 v[148:149], v[118:119], s[40:41] op_sel_hi:[1,0]
	v_pk_mul_f32 v[146:147], v[116:117], s[40:41] op_sel_hi:[1,0]
	s_mov_b32 s6, 0x40000
	v_cvt_pk_bf16_f32 v146, v146, v147
	v_cvt_pk_bf16_f32 v147, v148, v149
	v_cvt_pk_bf16_f32 v149, v152, v153
	v_add_co_u32_e32 v152, vcc, s65, v136
	v_cvt_pk_bf16_f32 v148, v154, v155
	s_nop 0
	v_addc_co_u32_e32 v153, vcc, 0, v137, vcc
	global_store_dwordx4 v[152:153], v[146:149], off
	v_pk_mul_f32 v[154:155], v[82:83], s[40:41] op_sel_hi:[1,0]
	s_nop 0
	v_pk_mul_f32 v[148:149], v[86:87], s[40:41] op_sel_hi:[1,0]
	v_pk_mul_f32 v[146:147], v[84:85], s[40:41] op_sel_hi:[1,0]
	s_nop 0
	v_cvt_pk_bf16_f32 v146, v146, v147
	v_cvt_pk_bf16_f32 v147, v148, v149
	v_cvt_pk_bf16_f32 v148, v156, v157
	v_cvt_pk_bf16_f32 v149, v154, v155
	global_store_dwordx4 v[152:153], v[146:149], off offset:256
	v_pk_mul_f32 v[152:153], v[106:107], s[40:41] op_sel_hi:[1,0]
	v_pk_mul_f32 v[154:155], v[104:105], s[40:41] op_sel_hi:[1,0]
	v_pk_mul_f32 v[148:149], v[110:111], s[40:41] op_sel_hi:[1,0]
	v_pk_mul_f32 v[146:147], v[108:109], s[40:41] op_sel_hi:[1,0]
	v_pk_mul_f32 v[156:157], v[72:73], s[40:41] op_sel_hi:[1,0]
	v_cvt_pk_bf16_f32 v146, v146, v147
	v_cvt_pk_bf16_f32 v147, v148, v149
	v_cvt_pk_bf16_f32 v149, v152, v153
	v_add_co_u32_e32 v152, vcc, s66, v136
	v_cvt_pk_bf16_f32 v148, v154, v155
	s_nop 0
	v_addc_co_u32_e32 v153, vcc, 0, v137, vcc
	global_store_dwordx4 v[152:153], v[146:149], off
	v_pk_mul_f32 v[154:155], v[74:75], s[40:41] op_sel_hi:[1,0]
	s_nop 0
	v_pk_mul_f32 v[148:149], v[78:79], s[40:41] op_sel_hi:[1,0]
	v_pk_mul_f32 v[146:147], v[76:77], s[40:41] op_sel_hi:[1,0]
	s_nop 0
	v_cvt_pk_bf16_f32 v146, v146, v147
	v_cvt_pk_bf16_f32 v147, v148, v149
	v_cvt_pk_bf16_f32 v148, v156, v157
	v_cvt_pk_bf16_f32 v149, v154, v155
	global_store_dwordx4 v[152:153], v[146:149], off offset:256
	v_pk_mul_f32 v[152:153], v[98:99], s[40:41] op_sel_hi:[1,0]
	v_pk_mul_f32 v[154:155], v[96:97], s[40:41] op_sel_hi:[1,0]
	v_pk_mul_f32 v[148:149], v[102:103], s[40:41] op_sel_hi:[1,0]
	v_pk_mul_f32 v[146:147], v[100:101], s[40:41] op_sel_hi:[1,0]
	v_pk_mul_f32 v[156:157], v[64:65], s[40:41] op_sel_hi:[1,0]
	v_cvt_pk_bf16_f32 v146, v146, v147
	v_cvt_pk_bf16_f32 v147, v148, v149
	v_cvt_pk_bf16_f32 v149, v152, v153
	v_add_co_u32_e32 v152, vcc, s64, v136
	v_cvt_pk_bf16_f32 v148, v154, v155
	s_nop 0
	v_addc_co_u32_e32 v153, vcc, 0, v137, vcc
	global_store_dwordx4 v[152:153], v[146:149], off
	v_pk_mul_f32 v[154:155], v[66:67], s[40:41] op_sel_hi:[1,0]
	s_nop 0
	v_pk_mul_f32 v[148:149], v[70:71], s[40:41] op_sel_hi:[1,0]
	v_pk_mul_f32 v[146:147], v[68:69], s[40:41] op_sel_hi:[1,0]
	s_nop 0
	v_cvt_pk_bf16_f32 v146, v146, v147
	v_cvt_pk_bf16_f32 v147, v148, v149
	v_cvt_pk_bf16_f32 v148, v156, v157
	v_cvt_pk_bf16_f32 v149, v154, v155
	global_store_dwordx4 v[152:153], v[146:149], off offset:256
	v_pk_mul_f32 v[152:153], v[58:59], s[40:41] op_sel_hi:[1,0]
	v_pk_mul_f32 v[154:155], v[56:57], s[40:41] op_sel_hi:[1,0]
	v_pk_mul_f32 v[148:149], v[62:63], s[40:41] op_sel_hi:[1,0]
	v_pk_mul_f32 v[146:147], v[60:61], s[40:41] op_sel_hi:[1,0]
	v_pk_mul_f32 v[156:157], v[24:25], s[40:41] op_sel_hi:[1,0]
	v_cvt_pk_bf16_f32 v146, v146, v147
	v_cvt_pk_bf16_f32 v147, v148, v149
	v_cvt_pk_bf16_f32 v149, v152, v153
	v_add_co_u32_e32 v152, vcc, s6, v136
	v_cvt_pk_bf16_f32 v148, v154, v155
	s_nop 0
	v_addc_co_u32_e32 v153, vcc, 0, v137, vcc
	global_store_dwordx4 v[152:153], v[146:149], off
	v_pk_mul_f32 v[154:155], v[26:27], s[40:41] op_sel_hi:[1,0]
	s_mov_b32 s6, 0x48000
	v_pk_mul_f32 v[148:149], v[30:31], s[40:41] op_sel_hi:[1,0]
	v_pk_mul_f32 v[146:147], v[28:29], s[40:41] op_sel_hi:[1,0]
	s_nop 0
	v_cvt_pk_bf16_f32 v146, v146, v147
	v_cvt_pk_bf16_f32 v147, v148, v149
	v_cvt_pk_bf16_f32 v148, v156, v157
	v_cvt_pk_bf16_f32 v149, v154, v155
	global_store_dwordx4 v[152:153], v[146:149], off offset:256
	v_pk_mul_f32 v[152:153], v[50:51], s[40:41] op_sel_hi:[1,0]
	v_pk_mul_f32 v[154:155], v[48:49], s[40:41] op_sel_hi:[1,0]
	v_pk_mul_f32 v[148:149], v[54:55], s[40:41] op_sel_hi:[1,0]
	v_pk_mul_f32 v[146:147], v[52:53], s[40:41] op_sel_hi:[1,0]
	v_pk_mul_f32 v[156:157], v[16:17], s[40:41] op_sel_hi:[1,0]
	v_cvt_pk_bf16_f32 v146, v146, v147
	v_cvt_pk_bf16_f32 v147, v148, v149
	v_cvt_pk_bf16_f32 v149, v152, v153
	v_add_co_u32_e32 v152, vcc, s6, v136
	v_cvt_pk_bf16_f32 v148, v154, v155
	s_nop 0
	v_addc_co_u32_e32 v153, vcc, 0, v137, vcc
	global_store_dwordx4 v[152:153], v[146:149], off
	v_pk_mul_f32 v[154:155], v[18:19], s[40:41] op_sel_hi:[1,0]
	s_mov_b32 s6, 0x50000
	v_pk_mul_f32 v[148:149], v[22:23], s[40:41] op_sel_hi:[1,0]
	v_pk_mul_f32 v[146:147], v[20:21], s[40:41] op_sel_hi:[1,0]
	s_nop 0
	v_cvt_pk_bf16_f32 v146, v146, v147
	v_cvt_pk_bf16_f32 v147, v148, v149
	v_cvt_pk_bf16_f32 v148, v156, v157
	v_cvt_pk_bf16_f32 v149, v154, v155
	global_store_dwordx4 v[152:153], v[146:149], off offset:256
	v_pk_mul_f32 v[152:153], v[42:43], s[40:41] op_sel_hi:[1,0]
	v_pk_mul_f32 v[154:155], v[40:41], s[40:41] op_sel_hi:[1,0]
	v_pk_mul_f32 v[148:149], v[46:47], s[40:41] op_sel_hi:[1,0]
	v_pk_mul_f32 v[146:147], v[44:45], s[40:41] op_sel_hi:[1,0]
	v_pk_mul_f32 v[156:157], v[8:9], s[40:41] op_sel_hi:[1,0]
	v_cvt_pk_bf16_f32 v146, v146, v147
	v_cvt_pk_bf16_f32 v147, v148, v149
	v_cvt_pk_bf16_f32 v149, v152, v153
	v_add_co_u32_e32 v152, vcc, s6, v136
	v_cvt_pk_bf16_f32 v148, v154, v155
	s_nop 0
	v_addc_co_u32_e32 v153, vcc, 0, v137, vcc
	global_store_dwordx4 v[152:153], v[146:149], off
	v_pk_mul_f32 v[154:155], v[10:11], s[40:41] op_sel_hi:[1,0]
	s_mov_b32 s6, 0x58000
	v_pk_mul_f32 v[148:149], v[14:15], s[40:41] op_sel_hi:[1,0]
	v_pk_mul_f32 v[146:147], v[12:13], s[40:41] op_sel_hi:[1,0]
	v_add_co_u32_e32 v136, vcc, s6, v136
	v_cvt_pk_bf16_f32 v146, v146, v147
	v_cvt_pk_bf16_f32 v147, v148, v149
	v_cvt_pk_bf16_f32 v148, v156, v157
	v_cvt_pk_bf16_f32 v149, v154, v155
	global_store_dwordx4 v[152:153], v[146:149], off offset:256
	v_pk_mul_f32 v[152:153], v[34:35], s[40:41] op_sel_hi:[1,0]
	v_pk_mul_f32 v[154:155], v[32:33], s[40:41] op_sel_hi:[1,0]
	v_pk_mul_f32 v[148:149], v[38:39], s[40:41] op_sel_hi:[1,0]
	v_pk_mul_f32 v[146:147], v[36:37], s[40:41] op_sel_hi:[1,0]
	v_addc_co_u32_e32 v137, vcc, 0, v137, vcc
	v_cvt_pk_bf16_f32 v146, v146, v147
	v_cvt_pk_bf16_f32 v147, v148, v149
	v_cvt_pk_bf16_f32 v148, v154, v155
	v_cvt_pk_bf16_f32 v149, v152, v153
	global_store_dwordx4 v[136:137], v[146:149], off
	v_pk_mul_f32 v[152:153], v[2:3], s[40:41] op_sel_hi:[1,0]
	v_pk_mul_f32 v[154:155], v[0:1], s[40:41] op_sel_hi:[1,0]
	v_pk_mul_f32 v[148:149], v[6:7], s[40:41] op_sel_hi:[1,0]
	v_pk_mul_f32 v[146:147], v[4:5], s[40:41] op_sel_hi:[1,0]
	s_and_b64 vcc, exec, s[42:43]
	v_cvt_pk_bf16_f32 v146, v146, v147
	v_cvt_pk_bf16_f32 v147, v148, v149
	v_cvt_pk_bf16_f32 v148, v154, v155
	v_cvt_pk_bf16_f32 v149, v152, v153
	global_store_dwordx4 v[136:137], v[146:149], off offset:256
	s_cbranch_vccnz .LBB0_761
	v_mov_b32_e32 v0, 0
	s_mov_b32 s77, s28
	s_mov_b32 s81, s82
	s_mov_b64 s[4:5], s[38:39]
	s_mov_b64 s[26:27], s[34:35]
	s_mov_b32 s80, s83
	v_mov_b32_e32 v1, v0
	v_mov_b32_e32 v2, v0
	v_mov_b32_e32 v3, v0
	v_mov_b32_e32 v4, v0
	v_mov_b32_e32 v5, v0
	v_mov_b32_e32 v6, v0
	v_mov_b32_e32 v7, v0
	v_mov_b32_e32 v8, v0
	v_mov_b32_e32 v9, v0
	v_mov_b32_e32 v10, v0
	v_mov_b32_e32 v11, v0
	v_mov_b32_e32 v12, v0
	v_mov_b32_e32 v13, v0
	v_mov_b32_e32 v14, v0
	v_mov_b32_e32 v15, v0
	v_mov_b32_e32 v16, v0
	v_mov_b32_e32 v17, v0
	v_mov_b32_e32 v18, v0
	v_mov_b32_e32 v19, v0
	v_mov_b32_e32 v20, v0
	v_mov_b32_e32 v21, v0
	v_mov_b32_e32 v22, v0
	v_mov_b32_e32 v23, v0
	v_mov_b32_e32 v24, v0
	v_mov_b32_e32 v25, v0
	v_mov_b32_e32 v26, v0
	v_mov_b32_e32 v27, v0
	v_mov_b32_e32 v28, v0
	v_mov_b32_e32 v29, v0
	v_mov_b32_e32 v30, v0
	v_mov_b32_e32 v31, v0
	v_mov_b32_e32 v32, v0
	v_mov_b32_e32 v33, v0
	v_mov_b32_e32 v34, v0
	v_mov_b32_e32 v35, v0
	v_mov_b32_e32 v36, v0
	v_mov_b32_e32 v37, v0
	v_mov_b32_e32 v38, v0
	v_mov_b32_e32 v39, v0
	v_mov_b32_e32 v40, v0
	v_mov_b32_e32 v41, v0
	v_mov_b32_e32 v42, v0
	v_mov_b32_e32 v43, v0
	v_mov_b32_e32 v44, v0
	v_mov_b32_e32 v45, v0
	v_mov_b32_e32 v46, v0
	v_mov_b32_e32 v47, v0
	v_mov_b32_e32 v48, v0
	v_mov_b32_e32 v49, v0
	v_mov_b32_e32 v50, v0
	v_mov_b32_e32 v51, v0
	v_mov_b32_e32 v52, v0
	v_mov_b32_e32 v53, v0
	v_mov_b32_e32 v54, v0
	v_mov_b32_e32 v55, v0
	v_mov_b32_e32 v56, v0
	v_mov_b32_e32 v57, v0
	v_mov_b32_e32 v58, v0
	v_mov_b32_e32 v59, v0
	v_mov_b32_e32 v60, v0
	v_mov_b32_e32 v61, v0
	v_mov_b32_e32 v62, v0
	v_mov_b32_e32 v63, v0
	v_mov_b32_e32 v64, v0
	v_mov_b32_e32 v65, v0
	v_mov_b32_e32 v66, v0
	v_mov_b32_e32 v67, v0
	v_mov_b32_e32 v68, v0
	v_mov_b32_e32 v69, v0
	v_mov_b32_e32 v70, v0
	v_mov_b32_e32 v71, v0
	v_mov_b32_e32 v72, v0
	v_mov_b32_e32 v73, v0
	v_mov_b32_e32 v74, v0
	v_mov_b32_e32 v75, v0
	v_mov_b32_e32 v76, v0
	v_mov_b32_e32 v77, v0
	v_mov_b32_e32 v78, v0
	v_mov_b32_e32 v79, v0
	v_mov_b32_e32 v80, v0
	v_mov_b32_e32 v81, v0
	v_mov_b32_e32 v82, v0
	v_mov_b32_e32 v83, v0
	v_mov_b32_e32 v84, v0
	v_mov_b32_e32 v85, v0
	v_mov_b32_e32 v86, v0
	v_mov_b32_e32 v87, v0
	v_mov_b32_e32 v88, v0
	v_mov_b32_e32 v89, v0
	v_mov_b32_e32 v90, v0
	v_mov_b32_e32 v91, v0
	v_mov_b32_e32 v92, v0
	v_mov_b32_e32 v93, v0
	v_mov_b32_e32 v94, v0
	v_mov_b32_e32 v95, v0
	v_mov_b32_e32 v96, v0
	v_mov_b32_e32 v97, v0
	v_mov_b32_e32 v98, v0
	v_mov_b32_e32 v99, v0
	v_mov_b32_e32 v100, v0
	v_mov_b32_e32 v101, v0
	v_mov_b32_e32 v102, v0
	v_mov_b32_e32 v103, v0
	v_mov_b32_e32 v104, v0
	v_mov_b32_e32 v105, v0
	v_mov_b32_e32 v106, v0
	v_mov_b32_e32 v107, v0
	v_mov_b32_e32 v108, v0
	v_mov_b32_e32 v109, v0
	v_mov_b32_e32 v110, v0
	v_mov_b32_e32 v111, v0
	v_mov_b32_e32 v112, v0
	v_mov_b32_e32 v113, v0
	v_mov_b32_e32 v114, v0
	v_mov_b32_e32 v115, v0
	v_mov_b32_e32 v116, v0
	v_mov_b32_e32 v117, v0
	v_mov_b32_e32 v118, v0
	v_mov_b32_e32 v119, v0
	v_mov_b32_e32 v120, v0
	v_mov_b32_e32 v121, v0
	v_mov_b32_e32 v122, v0
	v_mov_b32_e32 v123, v0
	v_mov_b32_e32 v124, v0
	v_mov_b32_e32 v125, v0
	v_mov_b32_e32 v126, v0
	v_mov_b32_e32 v127, v0
	s_branch .LBB0_761

.LBB0_797:
	s_add_u32 s6, s28, s5
	s_addc_u32 s12, s29, 0
	s_add_u32 s19, s6, 0x100
	s_addc_u32 s23, s12, 0
	s_and_b64 s[10:11], s[48:49], exec
	s_cselect_b32 s55, s39, s23
	s_cselect_b32 s54, s38, s19
	s_add_u32 s5, s26, s5
	s_addc_u32 s10, s27, 0
	s_add_u32 s5, s5, 0x100
	s_addc_u32 s19, s10, 0
	s_add_i32 s23, 0, 0x10000
	s_and_b64 s[10:11], s[48:49], exec
	s_cselect_b32 s59, s45, s19
	s_cselect_b32 s58, s44, s5
	s_add_u32 s68, s6, 0x40080
	s_addc_u32 s69, s12, 0
	s_add_i32 s88, s23, s70
	s_add_i32 m0, s72, 0xc000
	s_add_i32 s89, s72, 0xe000
	s_add_i32 s87, 0, 0x14000
	s_add_i32 s86, s88, 0x2000
	s_add_u32 s52, s58, 0x80000
	v_add_u32_e32 v158, s23, v138
	s_addc_u32 s53, s59, 0
	s_add_i32 s19, s87, s70
	ds_read_b128 v[146:149], v158
	ds_read_b128 v[150:153], v158 offset:1024
	ds_read_b128 v[154:157], v158 offset:2048
	ds_read_b128 v[158:161], v158 offset:3072
	s_add_i32 s12, s19, 0x2000
	s_add_i32 s11, 0, 0x18000
	s_add_u32 s50, s54, 0x40000
	s_addc_u32 s51, s55, 0
	s_add_i32 s10, s11, s70
	s_add_i32 s6, 0, 0x1c000
	s_add_i32 s5, s10, 0x2000
	s_add_u32 s48, s58, 0x80080
	s_addc_u32 s49, s59, 0
	s_add_i32 s85, s6, s70
	s_add_i32 s31, s85, 0x2000
	v_lshl_add_u64 v[192:193], s[68:69], 0, v[128:129]
	ds_read_b128 v[162:165], v139
	ds_read_b128 v[166:169], v139 offset:1024
	ds_read_b128 v[170:173], v139 offset:2048
	ds_read_b128 v[174:177], v139 offset:3072
	ds_read_b128 v[178:181], v139 offset:4096
	ds_read_b128 v[182:185], v139 offset:5120
	ds_read_b128 v[194:197], v139 offset:6144
	ds_read_b128 v[206:209], v139 offset:7168
	global_load_lds_dwordx4 v[192:193], off
	v_lshl_add_u64 v[192:193], s[68:69], 0, v[132:133]
	s_mov_b32 m0, s89
	s_nop 0
	global_load_lds_dwordx4 v[192:193], off
	s_waitcnt lgkmcnt(8)
	s_barrier
	s_waitcnt lgkmcnt(7)
	v_mfma_f32_16x16x32_bf16 v[124:127], v[146:149], v[162:165], v[124:127]
	v_mfma_f32_16x16x32_bf16 v[120:123], v[154:157], v[162:165], v[120:123]
	s_waitcnt lgkmcnt(5)
	v_mfma_f32_16x16x32_bf16 v[116:119], v[146:149], v[170:173], v[116:119]
	v_mfma_f32_16x16x32_bf16 v[112:115], v[154:157], v[170:173], v[112:115]
	s_waitcnt lgkmcnt(3)
	v_mfma_f32_16x16x32_bf16 v[108:111], v[146:149], v[178:181], v[108:111]
	v_mfma_f32_16x16x32_bf16 v[104:107], v[154:157], v[178:181], v[104:107]
	s_waitcnt lgkmcnt(1)
	v_mfma_f32_16x16x32_bf16 v[100:103], v[146:149], v[194:197], v[100:103]
	v_mfma_f32_16x16x32_bf16 v[96:99], v[154:157], v[194:197], v[96:99]
	v_mfma_f32_16x16x32_bf16 v[124:127], v[150:153], v[166:169], v[124:127]
	v_mfma_f32_16x16x32_bf16 v[120:123], v[158:161], v[166:169], v[120:123]
	v_mfma_f32_16x16x32_bf16 v[116:119], v[150:153], v[174:177], v[116:119]
	v_mfma_f32_16x16x32_bf16 v[112:115], v[158:161], v[174:177], v[112:115]
	v_mfma_f32_16x16x32_bf16 v[108:111], v[150:153], v[182:185], v[108:111]
	v_mfma_f32_16x16x32_bf16 v[104:107], v[158:161], v[182:185], v[104:107]
	s_waitcnt lgkmcnt(0)
	v_mfma_f32_16x16x32_bf16 v[100:103], v[150:153], v[206:209], v[100:103]
	v_mfma_f32_16x16x32_bf16 v[96:99], v[158:161], v[206:209], v[96:99]
	s_barrier
	v_add_u32_e32 v192, s87, v138
	s_mov_b32 m0, s88
	ds_read_b128 v[210:213], v192
	ds_read_b128 v[214:217], v192 offset:1024
	ds_read_b128 v[218:221], v192 offset:2048
	ds_read_b128 v[222:225], v192 offset:3072
	v_lshl_add_u64 v[192:193], s[58:59], 0, v[130:131]
	global_load_lds_dwordx4 v[192:193], off
	v_lshl_add_u64 v[226:227], s[58:59], 0, v[134:135]
	s_mov_b32 m0, s86
	s_nop 0
	global_load_lds_dwordx4 v[226:227], off
	s_barrier
	s_waitcnt lgkmcnt(3)
	v_mfma_f32_16x16x32_bf16 v[92:95], v[210:213], v[162:165], v[92:95]
	s_waitcnt lgkmcnt(1)
	v_mfma_f32_16x16x32_bf16 v[88:91], v[218:221], v[162:165], v[88:91]
	v_mfma_f32_16x16x32_bf16 v[84:87], v[210:213], v[170:173], v[84:87]
	v_mfma_f32_16x16x32_bf16 v[80:83], v[218:221], v[170:173], v[80:83]
	v_mfma_f32_16x16x32_bf16 v[76:79], v[210:213], v[178:181], v[76:79]
	v_mfma_f32_16x16x32_bf16 v[72:75], v[218:221], v[178:181], v[72:75]
	v_mfma_f32_16x16x32_bf16 v[68:71], v[210:213], v[194:197], v[68:71]
	v_mfma_f32_16x16x32_bf16 v[64:67], v[218:221], v[194:197], v[64:67]
	v_mfma_f32_16x16x32_bf16 v[92:95], v[214:217], v[166:169], v[92:95]
	s_waitcnt lgkmcnt(0)
	v_mfma_f32_16x16x32_bf16 v[88:91], v[222:225], v[166:169], v[88:91]
	v_mfma_f32_16x16x32_bf16 v[84:87], v[214:217], v[174:177], v[84:87]
	v_mfma_f32_16x16x32_bf16 v[80:83], v[222:225], v[174:177], v[80:83]
	v_mfma_f32_16x16x32_bf16 v[76:79], v[214:217], v[182:185], v[76:79]
	v_mfma_f32_16x16x32_bf16 v[72:75], v[222:225], v[182:185], v[72:75]
	v_mfma_f32_16x16x32_bf16 v[68:71], v[214:217], v[206:209], v[68:71]
	v_mfma_f32_16x16x32_bf16 v[64:67], v[222:225], v[206:209], v[64:67]
	s_mov_b32 m0, s72
	v_lshl_add_u64 v[228:229], s[54:55], 0, v[128:129]
	s_barrier
	ds_read_b128 v[162:165], v139 offset:16384
	ds_read_b128 v[166:169], v139 offset:17408
	ds_read_b128 v[170:173], v139 offset:18432
	ds_read_b128 v[174:177], v139 offset:19456
	ds_read_b128 v[178:181], v139 offset:20480
	ds_read_b128 v[182:185], v139 offset:21504
	ds_read_b128 v[194:197], v139 offset:22528
	ds_read_b128 v[206:209], v139 offset:23552
	global_load_lds_dwordx4 v[228:229], off
	v_lshl_add_u64 v[230:231], s[54:55], 0, v[132:133]
	s_mov_b32 m0, s73
	s_nop 0
	global_load_lds_dwordx4 v[230:231], off
	s_barrier
	s_waitcnt lgkmcnt(7)
	v_mfma_f32_16x16x32_bf16 v[60:63], v[146:149], v[162:165], v[60:63]
	v_mfma_f32_16x16x32_bf16 v[56:59], v[154:157], v[162:165], v[56:59]
	s_waitcnt lgkmcnt(5)
	v_mfma_f32_16x16x32_bf16 v[52:55], v[146:149], v[170:173], v[52:55]
	v_mfma_f32_16x16x32_bf16 v[48:51], v[154:157], v[170:173], v[48:51]
	s_waitcnt lgkmcnt(3)
	v_mfma_f32_16x16x32_bf16 v[44:47], v[146:149], v[178:181], v[44:47]
	v_mfma_f32_16x16x32_bf16 v[40:43], v[154:157], v[178:181], v[40:43]
	s_waitcnt lgkmcnt(1)
	v_mfma_f32_16x16x32_bf16 v[36:39], v[146:149], v[194:197], v[36:39]
	v_mfma_f32_16x16x32_bf16 v[32:35], v[154:157], v[194:197], v[32:35]
	v_mfma_f32_16x16x32_bf16 v[60:63], v[150:153], v[166:169], v[60:63]
	v_mfma_f32_16x16x32_bf16 v[56:59], v[158:161], v[166:169], v[56:59]
	v_mfma_f32_16x16x32_bf16 v[52:55], v[150:153], v[174:177], v[52:55]
	v_mfma_f32_16x16x32_bf16 v[48:51], v[158:161], v[174:177], v[48:51]
	v_mfma_f32_16x16x32_bf16 v[44:47], v[150:153], v[182:185], v[44:47]
	v_mfma_f32_16x16x32_bf16 v[40:43], v[158:161], v[182:185], v[40:43]
	s_waitcnt lgkmcnt(0)
	v_mfma_f32_16x16x32_bf16 v[36:39], v[150:153], v[206:209], v[36:39]
	v_mfma_f32_16x16x32_bf16 v[32:35], v[158:161], v[206:209], v[32:35]
	s_barrier
	s_mov_b32 m0, s19
	v_lshl_add_u64 v[146:147], s[52:53], 0, v[130:131]
	global_load_lds_dwordx4 v[146:147], off
	v_lshl_add_u64 v[146:147], s[52:53], 0, v[134:135]
	s_mov_b32 m0, s12
	s_nop 0
	global_load_lds_dwordx4 v[146:147], off
	s_nop 0
	s_waitcnt vmcnt(6)
	s_barrier
	v_mfma_f32_16x16x32_bf16 v[28:31], v[210:213], v[162:165], v[28:31]
	v_mfma_f32_16x16x32_bf16 v[24:27], v[218:221], v[162:165], v[24:27]
	v_mfma_f32_16x16x32_bf16 v[20:23], v[210:213], v[170:173], v[20:23]
	v_mfma_f32_16x16x32_bf16 v[16:19], v[218:221], v[170:173], v[16:19]
	v_mfma_f32_16x16x32_bf16 v[12:15], v[210:213], v[178:181], v[12:15]
	v_mfma_f32_16x16x32_bf16 v[8:11], v[218:221], v[178:181], v[8:11]
	v_mfma_f32_16x16x32_bf16 v[4:7], v[210:213], v[194:197], v[4:7]
	v_mfma_f32_16x16x32_bf16 v[0:3], v[218:221], v[194:197], v[0:3]
	v_mfma_f32_16x16x32_bf16 v[28:31], v[214:217], v[166:169], v[28:31]
	v_mfma_f32_16x16x32_bf16 v[24:27], v[222:225], v[166:169], v[24:27]
	v_mfma_f32_16x16x32_bf16 v[20:23], v[214:217], v[174:177], v[20:23]
	v_mfma_f32_16x16x32_bf16 v[16:19], v[222:225], v[174:177], v[16:19]
	v_mfma_f32_16x16x32_bf16 v[12:15], v[214:217], v[182:185], v[12:15]
	v_mfma_f32_16x16x32_bf16 v[8:11], v[222:225], v[182:185], v[8:11]
	v_mfma_f32_16x16x32_bf16 v[4:7], v[214:217], v[206:209], v[4:7]
	v_mfma_f32_16x16x32_bf16 v[0:3], v[222:225], v[206:209], v[0:3]
	v_add_u32_e32 v158, s11, v138
	s_barrier
	ds_read_b128 v[146:149], v158
	ds_read_b128 v[150:153], v158 offset:1024
	ds_read_b128 v[154:157], v158 offset:2048
	ds_read_b128 v[158:161], v158 offset:3072
	s_mov_b32 m0, s74
	v_lshl_add_u64 v[210:211], s[50:51], 0, v[128:129]
	ds_read_b128 v[162:165], v139 offset:32768
	ds_read_b128 v[166:169], v139 offset:33792
	ds_read_b128 v[170:173], v139 offset:34816
	ds_read_b128 v[174:177], v139 offset:35840
	ds_read_b128 v[178:181], v139 offset:36864
	ds_read_b128 v[182:185], v139 offset:37888
	ds_read_b128 v[194:197], v139 offset:38912
	ds_read_b128 v[206:209], v139 offset:39936
	global_load_lds_dwordx4 v[210:211], off
	v_lshl_add_u64 v[210:211], s[50:51], 0, v[132:133]
	s_mov_b32 m0, s75
	s_nop 0
	global_load_lds_dwordx4 v[210:211], off
	s_waitcnt lgkmcnt(8)
	s_barrier
	s_waitcnt lgkmcnt(7)
	v_mfma_f32_16x16x32_bf16 v[124:127], v[146:149], v[162:165], v[124:127]
	v_mfma_f32_16x16x32_bf16 v[120:123], v[154:157], v[162:165], v[120:123]
	s_waitcnt lgkmcnt(5)
	v_mfma_f32_16x16x32_bf16 v[116:119], v[146:149], v[170:173], v[116:119]
	v_mfma_f32_16x16x32_bf16 v[112:115], v[154:157], v[170:173], v[112:115]
	s_waitcnt lgkmcnt(3)
	v_mfma_f32_16x16x32_bf16 v[108:111], v[146:149], v[178:181], v[108:111]
	v_mfma_f32_16x16x32_bf16 v[104:107], v[154:157], v[178:181], v[104:107]
	s_waitcnt lgkmcnt(1)
	v_mfma_f32_16x16x32_bf16 v[100:103], v[146:149], v[194:197], v[100:103]
	v_mfma_f32_16x16x32_bf16 v[96:99], v[154:157], v[194:197], v[96:99]
	v_mfma_f32_16x16x32_bf16 v[124:127], v[150:153], v[166:169], v[124:127]
	v_mfma_f32_16x16x32_bf16 v[120:123], v[158:161], v[166:169], v[120:123]
	v_mfma_f32_16x16x32_bf16 v[116:119], v[150:153], v[174:177], v[116:119]
	v_mfma_f32_16x16x32_bf16 v[112:115], v[158:161], v[174:177], v[112:115]
	v_mfma_f32_16x16x32_bf16 v[108:111], v[150:153], v[182:185], v[108:111]
	v_mfma_f32_16x16x32_bf16 v[104:107], v[158:161], v[182:185], v[104:107]
	s_waitcnt lgkmcnt(0)
	v_mfma_f32_16x16x32_bf16 v[100:103], v[150:153], v[206:209], v[100:103]
	v_mfma_f32_16x16x32_bf16 v[96:99], v[158:161], v[206:209], v[96:99]
	s_barrier
	s_mov_b32 m0, s10
	v_add_u32_e32 v222, s6, v138
	v_lshl_add_u64 v[192:193], v[192:193], 0, s[36:37]
	ds_read_b128 v[210:213], v222
	ds_read_b128 v[214:217], v222 offset:1024
	ds_read_b128 v[218:221], v222 offset:2048
	ds_read_b128 v[222:225], v222 offset:3072
	global_load_lds_dwordx4 v[192:193], off
	v_lshl_add_u64 v[192:193], v[226:227], 0, s[36:37]
	s_mov_b32 m0, s5
	s_nop 0
	global_load_lds_dwordx4 v[192:193], off
	s_barrier
	s_waitcnt lgkmcnt(3)
	v_mfma_f32_16x16x32_bf16 v[92:95], v[210:213], v[162:165], v[92:95]
	s_waitcnt lgkmcnt(1)
	v_mfma_f32_16x16x32_bf16 v[88:91], v[218:221], v[162:165], v[88:91]
	v_mfma_f32_16x16x32_bf16 v[84:87], v[210:213], v[170:173], v[84:87]
	v_mfma_f32_16x16x32_bf16 v[80:83], v[218:221], v[170:173], v[80:83]
	v_mfma_f32_16x16x32_bf16 v[76:79], v[210:213], v[178:181], v[76:79]
	v_mfma_f32_16x16x32_bf16 v[72:75], v[218:221], v[178:181], v[72:75]
	v_mfma_f32_16x16x32_bf16 v[68:71], v[210:213], v[194:197], v[68:71]
	v_mfma_f32_16x16x32_bf16 v[64:67], v[218:221], v[194:197], v[64:67]
	v_mfma_f32_16x16x32_bf16 v[92:95], v[214:217], v[166:169], v[92:95]
	s_waitcnt lgkmcnt(0)
	v_mfma_f32_16x16x32_bf16 v[88:91], v[222:225], v[166:169], v[88:91]
	v_mfma_f32_16x16x32_bf16 v[84:87], v[214:217], v[174:177], v[84:87]
	v_mfma_f32_16x16x32_bf16 v[80:83], v[222:225], v[174:177], v[80:83]
	v_mfma_f32_16x16x32_bf16 v[76:79], v[214:217], v[182:185], v[76:79]
	v_mfma_f32_16x16x32_bf16 v[72:75], v[222:225], v[182:185], v[72:75]
	v_mfma_f32_16x16x32_bf16 v[68:71], v[214:217], v[206:209], v[68:71]
	v_mfma_f32_16x16x32_bf16 v[64:67], v[222:225], v[206:209], v[64:67]
	s_mov_b32 m0, s80
	v_lshl_add_u64 v[192:193], v[228:229], 0, s[36:37]
	s_barrier
	ds_read_b128 v[162:165], v139 offset:49152
	ds_read_b128 v[166:169], v139 offset:50176
	ds_read_b128 v[170:173], v139 offset:51200
	ds_read_b128 v[174:177], v139 offset:52224
	ds_read_b128 v[178:181], v139 offset:53248
	ds_read_b128 v[182:185], v139 offset:54272
	ds_read_b128 v[194:197], v139 offset:55296
	ds_read_b128 v[206:209], v139 offset:56320
	global_load_lds_dwordx4 v[192:193], off
	v_lshl_add_u64 v[192:193], v[230:231], 0, s[36:37]
	s_mov_b32 m0, s81
	s_nop 0
	global_load_lds_dwordx4 v[192:193], off
	s_barrier
	s_waitcnt lgkmcnt(7)
	v_mfma_f32_16x16x32_bf16 v[60:63], v[146:149], v[162:165], v[60:63]
	v_mfma_f32_16x16x32_bf16 v[56:59], v[154:157], v[162:165], v[56:59]
	s_waitcnt lgkmcnt(5)
	v_mfma_f32_16x16x32_bf16 v[52:55], v[146:149], v[170:173], v[52:55]
	v_mfma_f32_16x16x32_bf16 v[48:51], v[154:157], v[170:173], v[48:51]
	s_waitcnt lgkmcnt(3)
	v_mfma_f32_16x16x32_bf16 v[44:47], v[146:149], v[178:181], v[44:47]
	v_mfma_f32_16x16x32_bf16 v[40:43], v[154:157], v[178:181], v[40:43]
	s_waitcnt lgkmcnt(1)
	v_mfma_f32_16x16x32_bf16 v[36:39], v[146:149], v[194:197], v[36:39]
	v_mfma_f32_16x16x32_bf16 v[32:35], v[154:157], v[194:197], v[32:35]
	v_mfma_f32_16x16x32_bf16 v[60:63], v[150:153], v[166:169], v[60:63]
	v_mfma_f32_16x16x32_bf16 v[56:59], v[158:161], v[166:169], v[56:59]
	v_mfma_f32_16x16x32_bf16 v[52:55], v[150:153], v[174:177], v[52:55]
	v_mfma_f32_16x16x32_bf16 v[48:51], v[158:161], v[174:177], v[48:51]
	v_mfma_f32_16x16x32_bf16 v[44:47], v[150:153], v[182:185], v[44:47]
	v_mfma_f32_16x16x32_bf16 v[40:43], v[158:161], v[182:185], v[40:43]
	s_waitcnt lgkmcnt(0)
	v_mfma_f32_16x16x32_bf16 v[36:39], v[150:153], v[206:209], v[36:39]
	v_mfma_f32_16x16x32_bf16 v[32:35], v[158:161], v[206:209], v[32:35]
	s_barrier
	s_mov_b32 m0, s85
	v_lshl_add_u64 v[146:147], s[48:49], 0, v[130:131]
	global_load_lds_dwordx4 v[146:147], off
	v_lshl_add_u64 v[146:147], s[48:49], 0, v[134:135]
	s_mov_b32 m0, s31
	s_nop 0
	global_load_lds_dwordx4 v[146:147], off
	s_nop 0
	s_waitcnt vmcnt(6)
	s_barrier
	v_mfma_f32_16x16x32_bf16 v[28:31], v[210:213], v[162:165], v[28:31]
	v_mfma_f32_16x16x32_bf16 v[24:27], v[218:221], v[162:165], v[24:27]
	v_mfma_f32_16x16x32_bf16 v[20:23], v[210:213], v[170:173], v[20:23]
	v_mfma_f32_16x16x32_bf16 v[16:19], v[218:221], v[170:173], v[16:19]
	v_mfma_f32_16x16x32_bf16 v[12:15], v[210:213], v[178:181], v[12:15]
	v_mfma_f32_16x16x32_bf16 v[8:11], v[218:221], v[178:181], v[8:11]
	v_mfma_f32_16x16x32_bf16 v[4:7], v[210:213], v[194:197], v[4:7]
	v_mfma_f32_16x16x32_bf16 v[0:3], v[218:221], v[194:197], v[0:3]
	v_mfma_f32_16x16x32_bf16 v[28:31], v[214:217], v[166:169], v[28:31]
	v_mfma_f32_16x16x32_bf16 v[24:27], v[222:225], v[166:169], v[24:27]
	v_mfma_f32_16x16x32_bf16 v[20:23], v[214:217], v[174:177], v[20:23]
	v_mfma_f32_16x16x32_bf16 v[16:19], v[222:225], v[174:177], v[16:19]
	v_mfma_f32_16x16x32_bf16 v[12:15], v[214:217], v[182:185], v[12:15]
	v_mfma_f32_16x16x32_bf16 v[8:11], v[222:225], v[182:185], v[8:11]
	v_mfma_f32_16x16x32_bf16 v[4:7], v[214:217], v[206:209], v[4:7]
	v_mfma_f32_16x16x32_bf16 v[0:3], v[222:225], v[206:209], v[0:3]
	s_movk_i32 s5, 0x100
	s_andn2_b64 vcc, exec, s[46:47]
	s_mov_b64 s[48:49], -1
	s_mov_b64 s[46:47], 0
	s_barrier
	s_cbranch_vccz .LBB0_797
	s_ashr_i32 s10, s71, 2
	s_ashr_i32 s11, s10, 31
	s_lshl_b64 s[10:11], s[10:11], 21
	s_add_u32 s5, s76, s10
	s_addc_u32 s6, s77, s11
	s_lshl_b32 s10, s71, 9
	s_and_b32 s10, s10, 0x600
	s_add_u32 s10, s5, s10
	s_addc_u32 s11, s6, 0
	s_ashr_i32 s5, s4, 31
	v_lshl_add_u64 v[146:147], s[10:11], 0, v[140:141]
	s_lshl_b64 s[10:11], s[4:5], 19
	v_lshl_add_u64 v[146:147], v[146:147], 0, s[10:11]
	v_lshl_add_u64 v[150:151], v[146:147], 0, v[136:137]
	v_cvt_pk_bf16_f32 v146, v124, v125
	v_cvt_pk_bf16_f32 v147, v126, v127
	v_cvt_pk_bf16_f32 v148, v120, v121
	v_cvt_pk_bf16_f32 v149, v122, v123
	global_store_dwordx4 v[150:151], v[146:149], off
	v_add_co_u32_e32 v152, vcc, s65, v150
	s_nop 0
	v_cvt_pk_bf16_f32 v146, v92, v93
	v_cvt_pk_bf16_f32 v147, v94, v95
	v_cvt_pk_bf16_f32 v148, v88, v89
	v_cvt_pk_bf16_f32 v149, v90, v91
	global_store_dwordx4 v[150:151], v[146:149], off offset:256
	v_addc_co_u32_e32 v153, vcc, 0, v151, vcc
	s_nop 0
	v_cvt_pk_bf16_f32 v146, v116, v117
	v_cvt_pk_bf16_f32 v147, v118, v119
	v_cvt_pk_bf16_f32 v148, v112, v113
	v_cvt_pk_bf16_f32 v149, v114, v115
	global_store_dwordx4 v[152:153], v[146:149], off
	s_mov_b32 s5, 0x40000
	s_nop 0
	v_cvt_pk_bf16_f32 v146, v84, v85
	v_cvt_pk_bf16_f32 v147, v86, v87
	v_cvt_pk_bf16_f32 v148, v80, v81
	v_cvt_pk_bf16_f32 v149, v82, v83
	global_store_dwordx4 v[152:153], v[146:149], off offset:256
	v_add_co_u32_e32 v152, vcc, s66, v150
	s_nop 0
	v_cvt_pk_bf16_f32 v146, v108, v109
	v_cvt_pk_bf16_f32 v147, v110, v111
	v_cvt_pk_bf16_f32 v148, v104, v105
	v_cvt_pk_bf16_f32 v149, v106, v107
	v_addc_co_u32_e32 v153, vcc, 0, v151, vcc
	global_store_dwordx4 v[152:153], v[146:149], off
	s_nop 1
	v_cvt_pk_bf16_f32 v146, v76, v77
	v_cvt_pk_bf16_f32 v147, v78, v79
	v_cvt_pk_bf16_f32 v148, v72, v73
	v_cvt_pk_bf16_f32 v149, v74, v75
	global_store_dwordx4 v[152:153], v[146:149], off offset:256
	v_add_co_u32_e32 v152, vcc, s64, v150
	s_nop 0
	v_cvt_pk_bf16_f32 v146, v100, v101
	v_cvt_pk_bf16_f32 v147, v102, v103
	v_cvt_pk_bf16_f32 v148, v96, v97
	v_cvt_pk_bf16_f32 v149, v98, v99
	v_addc_co_u32_e32 v153, vcc, 0, v151, vcc
	global_store_dwordx4 v[152:153], v[146:149], off
	s_nop 1
	v_cvt_pk_bf16_f32 v146, v68, v69
	v_cvt_pk_bf16_f32 v147, v70, v71
	v_cvt_pk_bf16_f32 v148, v64, v65
	v_cvt_pk_bf16_f32 v149, v66, v67
	global_store_dwordx4 v[152:153], v[146:149], off offset:256
	v_add_co_u32_e32 v152, vcc, s5, v150
	s_nop 0
	v_cvt_pk_bf16_f32 v146, v60, v61
	v_cvt_pk_bf16_f32 v147, v62, v63
	v_cvt_pk_bf16_f32 v148, v56, v57
	v_cvt_pk_bf16_f32 v149, v58, v59
	v_addc_co_u32_e32 v153, vcc, 0, v151, vcc
	global_store_dwordx4 v[152:153], v[146:149], off
	s_mov_b32 s5, 0x48000
	s_nop 0
	v_cvt_pk_bf16_f32 v146, v28, v29
	v_cvt_pk_bf16_f32 v147, v30, v31
	v_cvt_pk_bf16_f32 v148, v24, v25
	v_cvt_pk_bf16_f32 v149, v26, v27
	global_store_dwordx4 v[152:153], v[146:149], off offset:256
	v_add_co_u32_e32 v152, vcc, s5, v150
	s_nop 0
	v_cvt_pk_bf16_f32 v146, v52, v53
	v_cvt_pk_bf16_f32 v147, v54, v55
	v_cvt_pk_bf16_f32 v148, v48, v49
	v_cvt_pk_bf16_f32 v149, v50, v51
	v_addc_co_u32_e32 v153, vcc, 0, v151, vcc
	global_store_dwordx4 v[152:153], v[146:149], off
	s_mov_b32 s5, 0x50000
	s_nop 0
	v_cvt_pk_bf16_f32 v146, v20, v21
	v_cvt_pk_bf16_f32 v147, v22, v23
	v_cvt_pk_bf16_f32 v148, v16, v17
	v_cvt_pk_bf16_f32 v149, v18, v19
	global_store_dwordx4 v[152:153], v[146:149], off offset:256
	v_add_co_u32_e32 v152, vcc, s5, v150
	s_nop 0
	v_cvt_pk_bf16_f32 v146, v44, v45
	v_cvt_pk_bf16_f32 v147, v46, v47
	v_cvt_pk_bf16_f32 v148, v40, v41
	v_cvt_pk_bf16_f32 v149, v42, v43
	v_addc_co_u32_e32 v153, vcc, 0, v151, vcc
	s_mov_b32 s5, 0x58000
	global_store_dwordx4 v[152:153], v[146:149], off
	v_add_co_u32_e32 v150, vcc, s5, v150
	s_nop 0
	v_cvt_pk_bf16_f32 v146, v12, v13
	v_cvt_pk_bf16_f32 v147, v14, v15
	v_cvt_pk_bf16_f32 v148, v8, v9
	v_cvt_pk_bf16_f32 v149, v10, v11
	global_store_dwordx4 v[152:153], v[146:149], off offset:256
	v_addc_co_u32_e32 v151, vcc, 0, v151, vcc
	s_nop 0
	v_cvt_pk_bf16_f32 v146, v36, v37
	v_cvt_pk_bf16_f32 v147, v38, v39
	v_cvt_pk_bf16_f32 v148, v32, v33
	v_cvt_pk_bf16_f32 v149, v34, v35
	global_store_dwordx4 v[150:151], v[146:149], off
	s_and_b64 vcc, exec, s[42:43]
	s_nop 0
	v_cvt_pk_bf16_f32 v146, v4, v5
	v_cvt_pk_bf16_f32 v147, v6, v7
	v_cvt_pk_bf16_f32 v148, v0, v1
	v_cvt_pk_bf16_f32 v149, v2, v3
	global_store_dwordx4 v[150:151], v[146:149], off offset:256
	s_cbranch_vccnz .LBB0_785
	v_mov_b32_e32 v0, 0
	s_mov_b32 s4, s30
	s_mov_b32 s71, s83
	s_mov_b64 s[26:27], s[44:45]
	s_mov_b64 s[28:29], s[38:39]
	s_mov_b32 s82, s84
	v_mov_b32_e32 v1, v0
	v_mov_b32_e32 v2, v0
	v_mov_b32_e32 v3, v0
	v_mov_b32_e32 v4, v0
	v_mov_b32_e32 v5, v0
	v_mov_b32_e32 v6, v0
	v_mov_b32_e32 v7, v0
	v_mov_b32_e32 v8, v0
	v_mov_b32_e32 v9, v0
	v_mov_b32_e32 v10, v0
	v_mov_b32_e32 v11, v0
	v_mov_b32_e32 v12, v0
	v_mov_b32_e32 v13, v0
	v_mov_b32_e32 v14, v0
	v_mov_b32_e32 v15, v0
	v_mov_b32_e32 v16, v0
	v_mov_b32_e32 v17, v0
	v_mov_b32_e32 v18, v0
	v_mov_b32_e32 v19, v0
	v_mov_b32_e32 v20, v0
	v_mov_b32_e32 v21, v0
	v_mov_b32_e32 v22, v0
	v_mov_b32_e32 v23, v0
	v_mov_b32_e32 v24, v0
	v_mov_b32_e32 v25, v0
	v_mov_b32_e32 v26, v0
	v_mov_b32_e32 v27, v0
	v_mov_b32_e32 v28, v0
	v_mov_b32_e32 v29, v0
	v_mov_b32_e32 v30, v0
	v_mov_b32_e32 v31, v0
	v_mov_b32_e32 v32, v0
	v_mov_b32_e32 v33, v0
	v_mov_b32_e32 v34, v0
	v_mov_b32_e32 v35, v0
	v_mov_b32_e32 v36, v0
	v_mov_b32_e32 v37, v0
	v_mov_b32_e32 v38, v0
	v_mov_b32_e32 v39, v0
	v_mov_b32_e32 v40, v0
	v_mov_b32_e32 v41, v0
	v_mov_b32_e32 v42, v0
	v_mov_b32_e32 v43, v0
	v_mov_b32_e32 v44, v0
	v_mov_b32_e32 v45, v0
	v_mov_b32_e32 v46, v0
	v_mov_b32_e32 v47, v0
	v_mov_b32_e32 v48, v0
	v_mov_b32_e32 v49, v0
	v_mov_b32_e32 v50, v0
	v_mov_b32_e32 v51, v0
	v_mov_b32_e32 v52, v0
	v_mov_b32_e32 v53, v0
	v_mov_b32_e32 v54, v0
	v_mov_b32_e32 v55, v0
	v_mov_b32_e32 v56, v0
	v_mov_b32_e32 v57, v0
	v_mov_b32_e32 v58, v0
	v_mov_b32_e32 v59, v0
	v_mov_b32_e32 v60, v0
	v_mov_b32_e32 v61, v0
	v_mov_b32_e32 v62, v0
	v_mov_b32_e32 v63, v0
	v_mov_b32_e32 v64, v0
	v_mov_b32_e32 v65, v0
	v_mov_b32_e32 v66, v0
	v_mov_b32_e32 v67, v0
	v_mov_b32_e32 v68, v0
	v_mov_b32_e32 v69, v0
	v_mov_b32_e32 v70, v0
	v_mov_b32_e32 v71, v0
	v_mov_b32_e32 v72, v0
	v_mov_b32_e32 v73, v0
	v_mov_b32_e32 v74, v0
	v_mov_b32_e32 v75, v0
	v_mov_b32_e32 v76, v0
	v_mov_b32_e32 v77, v0
	v_mov_b32_e32 v78, v0
	v_mov_b32_e32 v79, v0
	v_mov_b32_e32 v80, v0
	v_mov_b32_e32 v81, v0
	v_mov_b32_e32 v82, v0
	v_mov_b32_e32 v83, v0
	v_mov_b32_e32 v84, v0
	v_mov_b32_e32 v85, v0
	v_mov_b32_e32 v86, v0
	v_mov_b32_e32 v87, v0
	v_mov_b32_e32 v88, v0
	v_mov_b32_e32 v89, v0
	v_mov_b32_e32 v90, v0
	v_mov_b32_e32 v91, v0
	v_mov_b32_e32 v92, v0
	v_mov_b32_e32 v93, v0
	v_mov_b32_e32 v94, v0
	v_mov_b32_e32 v95, v0
	v_mov_b32_e32 v96, v0
	v_mov_b32_e32 v97, v0
	v_mov_b32_e32 v98, v0
	v_mov_b32_e32 v99, v0
	v_mov_b32_e32 v100, v0
	v_mov_b32_e32 v101, v0
	v_mov_b32_e32 v102, v0
	v_mov_b32_e32 v103, v0
	v_mov_b32_e32 v104, v0
	v_mov_b32_e32 v105, v0
	v_mov_b32_e32 v106, v0
	v_mov_b32_e32 v107, v0
	v_mov_b32_e32 v108, v0
	v_mov_b32_e32 v109, v0
	v_mov_b32_e32 v110, v0
	v_mov_b32_e32 v111, v0
	v_mov_b32_e32 v112, v0
	v_mov_b32_e32 v113, v0
	v_mov_b32_e32 v114, v0
	v_mov_b32_e32 v115, v0
	v_mov_b32_e32 v116, v0
	v_mov_b32_e32 v117, v0
	v_mov_b32_e32 v118, v0
	v_mov_b32_e32 v119, v0
	v_mov_b32_e32 v120, v0
	v_mov_b32_e32 v121, v0
	v_mov_b32_e32 v122, v0
	v_mov_b32_e32 v123, v0
	v_mov_b32_e32 v124, v0
	v_mov_b32_e32 v125, v0
	v_mov_b32_e32 v126, v0
	v_mov_b32_e32 v127, v0
	s_branch .LBB0_785
